# v76 + P6 scan: sample-row recurrences hand-written, their loads issued ahead of the prompt item's loads and consumed under that latency (no serial sample tail)
# speedup vs baseline: 1.0010x; 1.0010x over previous
; #define LAS __attribute__((address_space(3)))
; __device__ __forceinline__ float bflo(unsigned w) { return __uint_as_float(w << 16); }
; __device__ __forceinline__ float bfhi(unsigned w) { return __uint_as_float(w & 0xffff0000u); }
; __device__ __forceinline__ void phase_scan(const Params& p, LAS unsigned char* lds) {
;     const int tid = threadIdx.x;
;     const unsigned* LU = (const unsigned*)(p.ws + WS_LA); bf16_t* YL = (bf16_t*)(p.ws + WS_YL);
;     LAS float* sA = (LAS float*)lds; LAS float* sH = sA + 512;
;     for (int item = blockIdx.x; item < 256; item += gridDim.x) {
;         const int b = item >> 6, c32 = tid & 31, ch = (item & 63) * 32 + c32, chunk = tid >> 5;
;         const size_t base = (size_t)(b * SEQ + chunk * 128) * LW + ch;
;         float h = 0.f, sla = 0.f;
;     ...
;     const int gt = blockIdx.x * NTHREADS + tid, NGT = gridDim.x * NTHREADS;
;     for (int i = gt; i < 128 * LW; i += NGT) { const int b = i >> 11, ch = i & 2047;
;         float h = p.in[I_SLH][i]; const size_t base = (size_t)(MPROMPT + b * 8) * LW + ch;
; #pragma unroll
;         for (int s = 0; s < 8; ++s) { const unsigned lw = LU[base + (size_t)s * LW]; const float la = bflo(lw), u = bfhi(lw); h = __expf(la) * h + u;
.Lipf_skip_5:
	s_cmpk_lt_i32 s2, 0x100
	s_cselect_b64 s[56:57], -1, 0
	s_cmpk_gt_i32 s2, 0xff
	s_waitcnt lgkmcnt(0)
	s_barrier
	s_cbranch_scc1 .LBB0_877
	v_lshrrev_b32_e32 v128, 5, v212
	v_and_b32_e32 v129, 31, v212
	v_lshlrev_b32_e32 v130, 20, v128
	v_lshlrev_b32_e32 v148, 2, v129
	v_or_b32_e32 v130, v130, v148
	v_add_u32_e32 v131, 0x2000, v130
	v_add_u32_e32 v132, 0x4000, v130
	v_add_u32_e32 v133, 0x6000, v130
	v_lshlrev_b32_e32 v134, 19, v128
	v_lshl_or_b32 v134, v129, 1, v134
	v_add_u32_e32 v135, 0x1000, v134
	v_add_u32_e32 v136, 0x2000, v134
	v_add_u32_e32 v137, 0x3000, v134
	v_readlane_b32 s68, v254, 47
	v_readlane_b32 s69, v254, 48
	v_lshrrev_b32_e32 v189, 11, v220
	v_and_b32_e32 v190, 0x7ff, v220
	v_lshlrev_b32_e32 v186, 16, v189
	v_lshl_or_b32 v186, v190, 2, v186
	v_lshlrev_b32_e32 v188, 15, v189
	v_lshl_or_b32 v188, v190, 1, v188
	v_lshlrev_b32_e32 v187, 2, v220
	v_readlane_b32 s74, v254, 13
	v_readlane_b32 s75, v254, 14
	s_add_u32 s76, s84, 0xad00000
	s_addc_u32 s77, s85, 0
	s_add_u32 s78, s84, 0x17b00000
	s_addc_u32 s79, s85, 0
	s_nop 1
	global_load_dword v192, v187, s[74:75]
	s_add_u32 s74, s74, 0x80000
	s_addc_u32 s75, s75, 0
	global_load_dword v193, v187, s[74:75]
	global_load_dword v194, v186, s[76:77]
	s_add_u32 s76, s76, 0x2000
	s_addc_u32 s77, s77, 0
	global_load_dword v195, v186, s[76:77]
	s_add_u32 s76, s76, 0x2000
	s_addc_u32 s77, s77, 0
	global_load_dword v196, v186, s[76:77]
	s_add_u32 s76, s76, 0x2000
	s_addc_u32 s77, s77, 0
	global_load_dword v197, v186, s[76:77]
	s_add_u32 s76, s76, 0x2000
	s_addc_u32 s77, s77, 0
	global_load_dword v198, v186, s[76:77]
	s_add_u32 s76, s76, 0x2000
	s_addc_u32 s77, s77, 0
	global_load_dword v199, v186, s[76:77]
	s_add_u32 s76, s76, 0x2000
	s_addc_u32 s77, s77, 0
	global_load_dword v200, v186, s[76:77]
	s_add_u32 s76, s76, 0x2000
	s_addc_u32 s77, s77, 0
	global_load_dword v201, v186, s[76:77]
	s_add_u32 s76, s76, 0x3f2000
	s_addc_u32 s77, s77, 0
	global_load_dword v202, v186, s[76:77]
	s_add_u32 s76, s76, 0x2000
	s_addc_u32 s77, s77, 0
	global_load_dword v203, v186, s[76:77]
	s_add_u32 s76, s76, 0x2000
	s_addc_u32 s77, s77, 0
	global_load_dword v204, v186, s[76:77]
	s_add_u32 s76, s76, 0x2000
	s_addc_u32 s77, s77, 0
	global_load_dword v205, v186, s[76:77]
	s_add_u32 s76, s76, 0x2000
	s_addc_u32 s77, s77, 0
	global_load_dword v206, v186, s[76:77]
	s_add_u32 s76, s76, 0x2000
	s_addc_u32 s77, s77, 0
	global_load_dword v207, v186, s[76:77]
	s_add_u32 s76, s76, 0x2000
	s_addc_u32 s77, s77, 0
	global_load_dword v208, v186, s[76:77]
	s_add_u32 s76, s76, 0x2000
	s_addc_u32 s77, s77, 0
	global_load_dword v209, v186, s[76:77]
	s_mov_b32 s73, 1

; __device__ __forceinline__ unsigned pk2(float lo, float hi) { unsigned r; asm("v_cvt_pk_bf16_f32 %0, %1, %2" : "=v"(r) : "v"(lo), "v"(hi)); return r; }
; __device__ __forceinline__ float bflo(unsigned w) { return __uint_as_float(w << 16); }
; __device__ __forceinline__ float bfhi(unsigned w) { return __uint_as_float(w & 0xffff0000u); }
; __device__ __forceinline__ void phase_scan(const Params& p, LAS unsigned char* lds) {
;     ...
;         const int b = item >> 6, c32 = tid & 31, ch = (item & 63) * 32 + c32, chunk = tid >> 5;
;         const size_t base = (size_t)(b * SEQ + chunk * 128) * LW + ch;
;         float h = 0.f, sla = 0.f;
; #pragma unroll 8
;         for (int s = 0; s < 128; ++s) { const unsigned lw = LU[base + (size_t)s * LW]; const float la = bflo(lw), u = bfhi(lw); h = __expf(la) * h + u; sla += la; }
;     ...
;     for (int i = gt; i < 128 * LW; i += NGT) { const int b = i >> 11, ch = i & 2047;
;         float h = p.in[I_SLH][i]; const size_t base = (size_t)(MPROMPT + b * 8) * LW + ch;
; #pragma unroll
;         for (int s = 0; s < 8; ++s) { const unsigned lw = LU[base + (size_t)s * LW]; const float la = bflo(lw), u = bfhi(lw); h = __expf(la) * h + u;
;             YL[base + (size_t)s * LW] = (bf16_t)(pk2(h, h) & 0xffffu); }
.Lscan_item:
	s_lshr_b32 s0, s33, 6
	s_and_b32 s1, s33, 63
	s_lshl_b32 s42, s0, 24
	s_lshl_b32 s43, s1, 7
	s_add_u32 s42, s42, s43
	s_add_u32 s64, s84, 0x6d00000
	s_addc_u32 s65, s85, 0
	s_add_u32 s64, s64, s42
	s_addc_u32 s65, s65, 0
	s_lshl_b32 s42, s0, 23
	s_lshl_b32 s43, s1, 6
	s_add_u32 s42, s42, s43
	s_add_u32 s66, s84, 0x15b00000
	s_addc_u32 s67, s85, 0
	s_add_u32 s66, s66, s42
	s_addc_u32 s67, s67, 0
	s_lshl_b32 s42, s0, 13
	s_add_u32 s42, s42, s43
	s_add_u32 s42, s42, s43
	s_add_u32 s70, s68, 0x4854000
	s_addc_u32 s71, s69, 0
	s_add_u32 s70, s70, s42
	s_addc_u32 s71, s71, 0
	global_load_dword v0, v130, s[64:65]
	global_load_dword v1, v131, s[64:65]
	global_load_dword v2, v132, s[64:65]
	global_load_dword v3, v133, s[64:65]
	s_add_u32 s64, s64, 0x8000
	s_addc_u32 s65, s65, 0
	global_load_dword v4, v130, s[64:65]
	global_load_dword v5, v131, s[64:65]
	global_load_dword v6, v132, s[64:65]
	global_load_dword v7, v133, s[64:65]
	s_add_u32 s64, s64, 0x8000
	s_addc_u32 s65, s65, 0
	global_load_dword v8, v130, s[64:65]
	global_load_dword v9, v131, s[64:65]
	global_load_dword v10, v132, s[64:65]
	global_load_dword v11, v133, s[64:65]
	s_add_u32 s64, s64, 0x8000
	s_addc_u32 s65, s65, 0
	global_load_dword v12, v130, s[64:65]
	global_load_dword v13, v131, s[64:65]
	global_load_dword v14, v132, s[64:65]
	global_load_dword v15, v133, s[64:65]
	s_add_u32 s64, s64, 0x8000
	s_addc_u32 s65, s65, 0
	global_load_dword v16, v130, s[64:65]
	global_load_dword v17, v131, s[64:65]
	global_load_dword v18, v132, s[64:65]
	global_load_dword v19, v133, s[64:65]
	s_add_u32 s64, s64, 0x8000
	s_addc_u32 s65, s65, 0
	global_load_dword v20, v130, s[64:65]
	global_load_dword v21, v131, s[64:65]
	global_load_dword v22, v132, s[64:65]
	global_load_dword v23, v133, s[64:65]
	s_add_u32 s64, s64, 0x8000
	s_addc_u32 s65, s65, 0
	global_load_dword v24, v130, s[64:65]
	global_load_dword v25, v131, s[64:65]
	global_load_dword v26, v132, s[64:65]
	global_load_dword v27, v133, s[64:65]
	s_add_u32 s64, s64, 0x8000
	s_addc_u32 s65, s65, 0
	global_load_dword v28, v130, s[64:65]
	global_load_dword v29, v131, s[64:65]
	global_load_dword v30, v132, s[64:65]
	global_load_dword v31, v133, s[64:65]
	s_add_u32 s64, s64, 0x8000
	s_addc_u32 s65, s65, 0
	global_load_dword v32, v130, s[64:65]
	global_load_dword v33, v131, s[64:65]
	global_load_dword v34, v132, s[64:65]
	global_load_dword v35, v133, s[64:65]
	s_add_u32 s64, s64, 0x8000
	s_addc_u32 s65, s65, 0
	global_load_dword v36, v130, s[64:65]
	global_load_dword v37, v131, s[64:65]
	global_load_dword v38, v132, s[64:65]
	global_load_dword v39, v133, s[64:65]
	s_add_u32 s64, s64, 0x8000
	s_addc_u32 s65, s65, 0
	global_load_dword v40, v130, s[64:65]
	global_load_dword v41, v131, s[64:65]
	global_load_dword v42, v132, s[64:65]
	global_load_dword v43, v133, s[64:65]
	s_add_u32 s64, s64, 0x8000
	s_addc_u32 s65, s65, 0
	global_load_dword v44, v130, s[64:65]
	global_load_dword v45, v131, s[64:65]
	global_load_dword v46, v132, s[64:65]
	global_load_dword v47, v133, s[64:65]
	s_add_u32 s64, s64, 0x8000
	s_addc_u32 s65, s65, 0
	global_load_dword v48, v130, s[64:65]
	global_load_dword v49, v131, s[64:65]
	global_load_dword v50, v132, s[64:65]
	global_load_dword v51, v133, s[64:65]
	s_add_u32 s64, s64, 0x8000
	s_addc_u32 s65, s65, 0
	global_load_dword v52, v130, s[64:65]
	global_load_dword v53, v131, s[64:65]
	global_load_dword v54, v132, s[64:65]
	global_load_dword v55, v133, s[64:65]
	s_add_u32 s64, s64, 0x8000
	s_addc_u32 s65, s65, 0
	global_load_dword v56, v130, s[64:65]
	global_load_dword v57, v131, s[64:65]
	global_load_dword v58, v132, s[64:65]
	global_load_dword v59, v133, s[64:65]
	s_add_u32 s64, s64, 0x8000
	s_addc_u32 s65, s65, 0
	global_load_dword v60, v130, s[64:65]
	global_load_dword v61, v131, s[64:65]
	global_load_dword v62, v132, s[64:65]
	global_load_dword v63, v133, s[64:65]
	s_add_u32 s64, s64, 0x8000
	s_addc_u32 s65, s65, 0
	s_cmp_eq_u32 s73, 1
	s_cbranch_scc0 .Lscan_nosample
	s_mov_b32 s73, 0
	s_waitcnt vmcnt(63)
	v_lshlrev_b32_e32 v180, 16, v194
	v_mul_f32_e32 v180, 0x3fb8aa3b, v180
	v_exp_f32_e32 v180, v180
	v_and_b32_e32 v194, 0xffff0000, v194
	v_lshlrev_b32_e32 v182, 16, v202
	v_mul_f32_e32 v182, 0x3fb8aa3b, v182
	v_exp_f32_e32 v182, v182
	v_and_b32_e32 v202, 0xffff0000, v202
	v_fma_f32 v192, v180, v192, v194
	v_cvt_pk_bf16_f32 v194, v192, v192
	v_fma_f32 v193, v182, v193, v202
	v_cvt_pk_bf16_f32 v202, v193, v193
	v_lshlrev_b32_e32 v180, 16, v195
	v_mul_f32_e32 v180, 0x3fb8aa3b, v180
	v_exp_f32_e32 v180, v180
	v_and_b32_e32 v195, 0xffff0000, v195
	v_lshlrev_b32_e32 v182, 16, v203
	v_mul_f32_e32 v182, 0x3fb8aa3b, v182
	v_exp_f32_e32 v182, v182
	v_and_b32_e32 v203, 0xffff0000, v203
	v_fma_f32 v192, v180, v192, v195
	v_cvt_pk_bf16_f32 v195, v192, v192
	v_fma_f32 v193, v182, v193, v203
	v_cvt_pk_bf16_f32 v203, v193, v193
	v_lshlrev_b32_e32 v180, 16, v196
	v_mul_f32_e32 v180, 0x3fb8aa3b, v180
	v_exp_f32_e32 v180, v180
	v_and_b32_e32 v196, 0xffff0000, v196
	v_lshlrev_b32_e32 v182, 16, v204
	v_mul_f32_e32 v182, 0x3fb8aa3b, v182
	v_exp_f32_e32 v182, v182
	v_and_b32_e32 v204, 0xffff0000, v204
	v_fma_f32 v192, v180, v192, v196
	v_cvt_pk_bf16_f32 v196, v192, v192
	v_fma_f32 v193, v182, v193, v204
	v_cvt_pk_bf16_f32 v204, v193, v193
	v_lshlrev_b32_e32 v180, 16, v197
	v_mul_f32_e32 v180, 0x3fb8aa3b, v180
	v_exp_f32_e32 v180, v180
	v_and_b32_e32 v197, 0xffff0000, v197
	v_lshlrev_b32_e32 v182, 16, v205
	v_mul_f32_e32 v182, 0x3fb8aa3b, v182
	v_exp_f32_e32 v182, v182
	v_and_b32_e32 v205, 0xffff0000, v205
	v_fma_f32 v192, v180, v192, v197
	v_cvt_pk_bf16_f32 v197, v192, v192
	v_fma_f32 v193, v182, v193, v205
	v_cvt_pk_bf16_f32 v205, v193, v193
; __device__ __forceinline__ unsigned pk2(float lo, float hi) { unsigned r; asm("v_cvt_pk_bf16_f32 %0, %1, %2" : "=v"(r) : "v"(lo), "v"(hi)); return r; }
; __device__ __forceinline__ float bflo(unsigned w) { return __uint_as_float(w << 16); }
; __device__ __forceinline__ float bfhi(unsigned w) { return __uint_as_float(w & 0xffff0000u); }
; __device__ __forceinline__ void phase_scan(const Params& p, LAS unsigned char* lds) {
;     ...
;         for (int s = 0; s < 128; ++s) { const unsigned lw = LU[base + (size_t)s * LW]; const float la = bflo(lw), u = bfhi(lw); h = __expf(la) * h + u; sla += la; }
;     ...
;     for (int i = gt; i < 128 * LW; i += NGT) { const int b = i >> 11, ch = i & 2047;
;         float h = p.in[I_SLH][i]; const size_t base = (size_t)(MPROMPT + b * 8) * LW + ch;
; #pragma unroll
;         for (int s = 0; s < 8; ++s) { const unsigned lw = LU[base + (size_t)s * LW]; const float la = bflo(lw), u = bfhi(lw); h = __expf(la) * h + u;
;             YL[base + (size_t)s * LW] = (bf16_t)(pk2(h, h) & 0xffffu); }
;         p.out[O_LHS + i] = h; }
	v_lshlrev_b32_e32 v180, 16, v198
	v_mul_f32_e32 v180, 0x3fb8aa3b, v180
	v_exp_f32_e32 v180, v180
	v_and_b32_e32 v198, 0xffff0000, v198
	v_lshlrev_b32_e32 v182, 16, v206
	v_mul_f32_e32 v182, 0x3fb8aa3b, v182
	v_exp_f32_e32 v182, v182
	v_and_b32_e32 v206, 0xffff0000, v206
	v_fma_f32 v192, v180, v192, v198
	v_cvt_pk_bf16_f32 v198, v192, v192
	v_fma_f32 v193, v182, v193, v206
	v_cvt_pk_bf16_f32 v206, v193, v193
	v_lshlrev_b32_e32 v180, 16, v199
	v_mul_f32_e32 v180, 0x3fb8aa3b, v180
	v_exp_f32_e32 v180, v180
	v_and_b32_e32 v199, 0xffff0000, v199
	v_lshlrev_b32_e32 v182, 16, v207
	v_mul_f32_e32 v182, 0x3fb8aa3b, v182
	v_exp_f32_e32 v182, v182
	v_and_b32_e32 v207, 0xffff0000, v207
	v_fma_f32 v192, v180, v192, v199
	v_cvt_pk_bf16_f32 v199, v192, v192
	v_fma_f32 v193, v182, v193, v207
	v_cvt_pk_bf16_f32 v207, v193, v193
	v_lshlrev_b32_e32 v180, 16, v200
	v_mul_f32_e32 v180, 0x3fb8aa3b, v180
	v_exp_f32_e32 v180, v180
	v_and_b32_e32 v200, 0xffff0000, v200
	v_lshlrev_b32_e32 v182, 16, v208
	v_mul_f32_e32 v182, 0x3fb8aa3b, v182
	v_exp_f32_e32 v182, v182
	v_and_b32_e32 v208, 0xffff0000, v208
	v_fma_f32 v192, v180, v192, v200
	v_cvt_pk_bf16_f32 v200, v192, v192
	v_fma_f32 v193, v182, v193, v208
	v_cvt_pk_bf16_f32 v208, v193, v193
	v_lshlrev_b32_e32 v180, 16, v201
	v_mul_f32_e32 v180, 0x3fb8aa3b, v180
	v_exp_f32_e32 v180, v180
	v_and_b32_e32 v201, 0xffff0000, v201
	v_lshlrev_b32_e32 v182, 16, v209
	v_mul_f32_e32 v182, 0x3fb8aa3b, v182
	v_exp_f32_e32 v182, v182
	v_and_b32_e32 v209, 0xffff0000, v209
	v_fma_f32 v192, v180, v192, v201
	v_cvt_pk_bf16_f32 v201, v192, v192
	v_fma_f32 v193, v182, v193, v209
	v_cvt_pk_bf16_f32 v209, v193, v193
	global_store_short v188, v194, s[78:79]
	s_add_u32 s78, s78, 0x1000
	s_addc_u32 s79, s79, 0
	global_store_short v188, v195, s[78:79]
	s_add_u32 s78, s78, 0x1000
	s_addc_u32 s79, s79, 0
	global_store_short v188, v196, s[78:79]
	s_add_u32 s78, s78, 0x1000
	s_addc_u32 s79, s79, 0
	global_store_short v188, v197, s[78:79]
	s_add_u32 s78, s78, 0x1000
	s_addc_u32 s79, s79, 0
	global_store_short v188, v198, s[78:79]
	s_add_u32 s78, s78, 0x1000
	s_addc_u32 s79, s79, 0
	global_store_short v188, v199, s[78:79]
	s_add_u32 s78, s78, 0x1000
	s_addc_u32 s79, s79, 0
	global_store_short v188, v200, s[78:79]
	s_add_u32 s78, s78, 0x1000
	s_addc_u32 s79, s79, 0
	global_store_short v188, v201, s[78:79]
	s_add_u32 s78, s78, 0x1f9000
	s_addc_u32 s79, s79, 0
	global_store_short v188, v202, s[78:79]
	s_add_u32 s78, s78, 0x1000
	s_addc_u32 s79, s79, 0
	global_store_short v188, v203, s[78:79]
	s_add_u32 s78, s78, 0x1000
	s_addc_u32 s79, s79, 0
	global_store_short v188, v204, s[78:79]
	s_add_u32 s78, s78, 0x1000
	s_addc_u32 s79, s79, 0
	global_store_short v188, v205, s[78:79]
	s_add_u32 s78, s78, 0x1000
	s_addc_u32 s79, s79, 0
	global_store_short v188, v206, s[78:79]
	s_add_u32 s78, s78, 0x1000
	s_addc_u32 s79, s79, 0
	global_store_short v188, v207, s[78:79]
	s_add_u32 s78, s78, 0x1000
	s_addc_u32 s79, s79, 0
	global_store_short v188, v208, s[78:79]
	s_add_u32 s78, s78, 0x1000
	s_addc_u32 s79, s79, 0
	global_store_short v188, v209, s[78:79]
	s_add_u32 s74, s68, 0x533c000
	s_addc_u32 s75, s69, 0
	global_store_dword v187, v192, s[74:75]
	s_add_u32 s74, s74, 0x80000
	s_addc_u32 s75, s75, 0
	global_store_dword v187, v193, s[74:75]
.Lscan_nosample:
	v_mov_b32_e32 v138, 0
	v_mov_b32_e32 v139, 0
	s_waitcnt vmcnt(63)
	v_lshlrev_b32_e32 v140, 16, v0
	v_and_b32_e32 v142, 0xffff0000, v0
	v_mul_f32_e32 v141, 0x3fb8aa3b, v140
	v_exp_f32_e32 v141, v141
	v_add_f32_e32 v139, v139, v140
	v_fma_f32 v138, v141, v138, v142
	global_load_dword v64, v130, s[64:65]
	s_waitcnt vmcnt(63)
	v_lshlrev_b32_e32 v143, 16, v1
	v_and_b32_e32 v145, 0xffff0000, v1
	v_mul_f32_e32 v144, 0x3fb8aa3b, v143
	v_exp_f32_e32 v144, v144
	v_add_f32_e32 v139, v139, v143
	v_fma_f32 v138, v144, v138, v145
	global_load_dword v65, v131, s[64:65]
	s_waitcnt vmcnt(63)
	v_lshlrev_b32_e32 v140, 16, v2
	v_and_b32_e32 v142, 0xffff0000, v2
	v_mul_f32_e32 v141, 0x3fb8aa3b, v140
	v_exp_f32_e32 v141, v141
	v_add_f32_e32 v139, v139, v140
	v_fma_f32 v138, v141, v138, v142
	global_load_dword v66, v132, s[64:65]
	s_waitcnt vmcnt(63)
	v_lshlrev_b32_e32 v143, 16, v3
	v_and_b32_e32 v145, 0xffff0000, v3
	v_mul_f32_e32 v144, 0x3fb8aa3b, v143
	v_exp_f32_e32 v144, v144
	v_add_f32_e32 v139, v139, v143
	v_fma_f32 v138, v144, v138, v145
	global_load_dword v67, v133, s[64:65]
	s_add_u32 s64, s64, 0x8000
	s_addc_u32 s65, s65, 0
	s_waitcnt vmcnt(63)
	v_lshlrev_b32_e32 v140, 16, v4
	v_and_b32_e32 v142, 0xffff0000, v4
	v_mul_f32_e32 v141, 0x3fb8aa3b, v140
	v_exp_f32_e32 v141, v141
	v_add_f32_e32 v139, v139, v140
	v_fma_f32 v138, v141, v138, v142
	global_load_dword v68, v130, s[64:65]
	s_waitcnt vmcnt(63)
	v_lshlrev_b32_e32 v143, 16, v5
	v_and_b32_e32 v145, 0xffff0000, v5
	v_mul_f32_e32 v144, 0x3fb8aa3b, v143
	v_exp_f32_e32 v144, v144
	v_add_f32_e32 v139, v139, v143
	v_fma_f32 v138, v144, v138, v145
	global_load_dword v69, v131, s[64:65]
	s_waitcnt vmcnt(63)
	v_lshlrev_b32_e32 v140, 16, v6
	v_and_b32_e32 v142, 0xffff0000, v6
	v_mul_f32_e32 v141, 0x3fb8aa3b, v140
	v_exp_f32_e32 v141, v141
	v_add_f32_e32 v139, v139, v140
	v_fma_f32 v138, v141, v138, v142
	global_load_dword v70, v132, s[64:65]
	s_waitcnt vmcnt(63)
	v_lshlrev_b32_e32 v143, 16, v7
	v_and_b32_e32 v145, 0xffff0000, v7
	v_mul_f32_e32 v144, 0x3fb8aa3b, v143
	v_exp_f32_e32 v144, v144
	v_add_f32_e32 v139, v139, v143
	v_fma_f32 v138, v144, v138, v145
	global_load_dword v71, v133, s[64:65]
	s_add_u32 s64, s64, 0x8000
	s_addc_u32 s65, s65, 0
	s_waitcnt vmcnt(63)
; __device__ __forceinline__ float bflo(unsigned w) { return __uint_as_float(w << 16); }
; __device__ __forceinline__ float bfhi(unsigned w) { return __uint_as_float(w & 0xffff0000u); }
; __device__ __forceinline__ void phase_scan(const Params& p, LAS unsigned char* lds) {
;     ...
;         float h = 0.f, sla = 0.f;
; #pragma unroll 8
;         for (int s = 0; s < 128; ++s) { const unsigned lw = LU[base + (size_t)s * LW]; const float la = bflo(lw), u = bfhi(lw); h = __expf(la) * h + u; sla += la; }
	v_lshlrev_b32_e32 v140, 16, v8
	v_and_b32_e32 v142, 0xffff0000, v8
	v_mul_f32_e32 v141, 0x3fb8aa3b, v140
	v_exp_f32_e32 v141, v141
	v_add_f32_e32 v139, v139, v140
	v_fma_f32 v138, v141, v138, v142
	global_load_dword v72, v130, s[64:65]
	s_waitcnt vmcnt(63)
	v_lshlrev_b32_e32 v143, 16, v9
	v_and_b32_e32 v145, 0xffff0000, v9
	v_mul_f32_e32 v144, 0x3fb8aa3b, v143
	v_exp_f32_e32 v144, v144
	v_add_f32_e32 v139, v139, v143
	v_fma_f32 v138, v144, v138, v145
	global_load_dword v73, v131, s[64:65]
	s_waitcnt vmcnt(63)
	v_lshlrev_b32_e32 v140, 16, v10
	v_and_b32_e32 v142, 0xffff0000, v10
	v_mul_f32_e32 v141, 0x3fb8aa3b, v140
	v_exp_f32_e32 v141, v141
	v_add_f32_e32 v139, v139, v140
	v_fma_f32 v138, v141, v138, v142
	global_load_dword v74, v132, s[64:65]
	s_waitcnt vmcnt(63)
	v_lshlrev_b32_e32 v143, 16, v11
	v_and_b32_e32 v145, 0xffff0000, v11
	v_mul_f32_e32 v144, 0x3fb8aa3b, v143
	v_exp_f32_e32 v144, v144
	v_add_f32_e32 v139, v139, v143
	v_fma_f32 v138, v144, v138, v145
	global_load_dword v75, v133, s[64:65]
	s_add_u32 s64, s64, 0x8000
	s_addc_u32 s65, s65, 0
	s_waitcnt vmcnt(63)
	v_lshlrev_b32_e32 v140, 16, v12
	v_and_b32_e32 v142, 0xffff0000, v12
	v_mul_f32_e32 v141, 0x3fb8aa3b, v140
	v_exp_f32_e32 v141, v141
	v_add_f32_e32 v139, v139, v140
	v_fma_f32 v138, v141, v138, v142
	global_load_dword v76, v130, s[64:65]
	s_waitcnt vmcnt(63)
	v_lshlrev_b32_e32 v143, 16, v13
	v_and_b32_e32 v145, 0xffff0000, v13
	v_mul_f32_e32 v144, 0x3fb8aa3b, v143
	v_exp_f32_e32 v144, v144
	v_add_f32_e32 v139, v139, v143
	v_fma_f32 v138, v144, v138, v145
	global_load_dword v77, v131, s[64:65]
	s_waitcnt vmcnt(63)
	v_lshlrev_b32_e32 v140, 16, v14
	v_and_b32_e32 v142, 0xffff0000, v14
	v_mul_f32_e32 v141, 0x3fb8aa3b, v140
	v_exp_f32_e32 v141, v141
	v_add_f32_e32 v139, v139, v140
	v_fma_f32 v138, v141, v138, v142
	global_load_dword v78, v132, s[64:65]
	s_waitcnt vmcnt(63)
	v_lshlrev_b32_e32 v143, 16, v15
	v_and_b32_e32 v145, 0xffff0000, v15
	v_mul_f32_e32 v144, 0x3fb8aa3b, v143
	v_exp_f32_e32 v144, v144
	v_add_f32_e32 v139, v139, v143
	v_fma_f32 v138, v144, v138, v145
	global_load_dword v79, v133, s[64:65]
	s_add_u32 s64, s64, 0x8000
	s_addc_u32 s65, s65, 0
	s_waitcnt vmcnt(63)
	v_lshlrev_b32_e32 v140, 16, v16
	v_and_b32_e32 v142, 0xffff0000, v16
	v_mul_f32_e32 v141, 0x3fb8aa3b, v140
	v_exp_f32_e32 v141, v141
	v_add_f32_e32 v139, v139, v140
	v_fma_f32 v138, v141, v138, v142
	global_load_dword v80, v130, s[64:65]
	s_waitcnt vmcnt(63)
	v_lshlrev_b32_e32 v143, 16, v17
	v_and_b32_e32 v145, 0xffff0000, v17
	v_mul_f32_e32 v144, 0x3fb8aa3b, v143
	v_exp_f32_e32 v144, v144
	v_add_f32_e32 v139, v139, v143
	v_fma_f32 v138, v144, v138, v145
	global_load_dword v81, v131, s[64:65]
	s_waitcnt vmcnt(63)
	v_lshlrev_b32_e32 v140, 16, v18
	v_and_b32_e32 v142, 0xffff0000, v18
	v_mul_f32_e32 v141, 0x3fb8aa3b, v140
	v_exp_f32_e32 v141, v141
	v_add_f32_e32 v139, v139, v140
	v_fma_f32 v138, v141, v138, v142
	global_load_dword v82, v132, s[64:65]
	s_waitcnt vmcnt(63)
	v_lshlrev_b32_e32 v143, 16, v19
	v_and_b32_e32 v145, 0xffff0000, v19
	v_mul_f32_e32 v144, 0x3fb8aa3b, v143
	v_exp_f32_e32 v144, v144
	v_add_f32_e32 v139, v139, v143
	v_fma_f32 v138, v144, v138, v145
	global_load_dword v83, v133, s[64:65]
	s_add_u32 s64, s64, 0x8000
	s_addc_u32 s65, s65, 0
	s_waitcnt vmcnt(63)
	v_lshlrev_b32_e32 v140, 16, v20
	v_and_b32_e32 v142, 0xffff0000, v20
	v_mul_f32_e32 v141, 0x3fb8aa3b, v140
	v_exp_f32_e32 v141, v141
	v_add_f32_e32 v139, v139, v140
	v_fma_f32 v138, v141, v138, v142
	global_load_dword v84, v130, s[64:65]
	s_waitcnt vmcnt(63)
	v_lshlrev_b32_e32 v143, 16, v21
	v_and_b32_e32 v145, 0xffff0000, v21
	v_mul_f32_e32 v144, 0x3fb8aa3b, v143
	v_exp_f32_e32 v144, v144
	v_add_f32_e32 v139, v139, v143
	v_fma_f32 v138, v144, v138, v145
	global_load_dword v85, v131, s[64:65]
	s_waitcnt vmcnt(63)
	v_lshlrev_b32_e32 v140, 16, v22
	v_and_b32_e32 v142, 0xffff0000, v22
	v_mul_f32_e32 v141, 0x3fb8aa3b, v140
	v_exp_f32_e32 v141, v141
	v_add_f32_e32 v139, v139, v140
	v_fma_f32 v138, v141, v138, v142
	global_load_dword v86, v132, s[64:65]
	s_waitcnt vmcnt(63)
	v_lshlrev_b32_e32 v143, 16, v23
	v_and_b32_e32 v145, 0xffff0000, v23
	v_mul_f32_e32 v144, 0x3fb8aa3b, v143
	v_exp_f32_e32 v144, v144
	v_add_f32_e32 v139, v139, v143
	v_fma_f32 v138, v144, v138, v145
	global_load_dword v87, v133, s[64:65]
	s_add_u32 s64, s64, 0x8000
	s_addc_u32 s65, s65, 0
	s_waitcnt vmcnt(63)
	v_lshlrev_b32_e32 v140, 16, v24
	v_and_b32_e32 v142, 0xffff0000, v24
	v_mul_f32_e32 v141, 0x3fb8aa3b, v140
	v_exp_f32_e32 v141, v141
	v_add_f32_e32 v139, v139, v140
	v_fma_f32 v138, v141, v138, v142
	global_load_dword v88, v130, s[64:65]
	s_waitcnt vmcnt(63)
	v_lshlrev_b32_e32 v143, 16, v25
	v_and_b32_e32 v145, 0xffff0000, v25
	v_mul_f32_e32 v144, 0x3fb8aa3b, v143
	v_exp_f32_e32 v144, v144
	v_add_f32_e32 v139, v139, v143
	v_fma_f32 v138, v144, v138, v145
	global_load_dword v89, v131, s[64:65]
	s_waitcnt vmcnt(63)
	v_lshlrev_b32_e32 v140, 16, v26
	v_and_b32_e32 v142, 0xffff0000, v26
	v_mul_f32_e32 v141, 0x3fb8aa3b, v140
	v_exp_f32_e32 v141, v141
	v_add_f32_e32 v139, v139, v140
	v_fma_f32 v138, v141, v138, v142
	global_load_dword v90, v132, s[64:65]
	s_waitcnt vmcnt(63)
	v_lshlrev_b32_e32 v143, 16, v27
	v_and_b32_e32 v145, 0xffff0000, v27
	v_mul_f32_e32 v144, 0x3fb8aa3b, v143
	v_exp_f32_e32 v144, v144
	v_add_f32_e32 v139, v139, v143
	v_fma_f32 v138, v144, v138, v145
	global_load_dword v91, v133, s[64:65]
	s_add_u32 s64, s64, 0x8000
	s_addc_u32 s65, s65, 0
	s_waitcnt vmcnt(63)
	v_lshlrev_b32_e32 v140, 16, v28
	v_and_b32_e32 v142, 0xffff0000, v28
	v_mul_f32_e32 v141, 0x3fb8aa3b, v140
	v_exp_f32_e32 v141, v141
	v_add_f32_e32 v139, v139, v140
	v_fma_f32 v138, v141, v138, v142
	global_load_dword v92, v130, s[64:65]
	s_waitcnt vmcnt(63)
; __device__ __forceinline__ float bflo(unsigned w) { return __uint_as_float(w << 16); }
; __device__ __forceinline__ float bfhi(unsigned w) { return __uint_as_float(w & 0xffff0000u); }
; __device__ __forceinline__ void phase_scan(const Params& p, LAS unsigned char* lds) {
;     ...
;         float h = 0.f, sla = 0.f;
; #pragma unroll 8
;         for (int s = 0; s < 128; ++s) { const unsigned lw = LU[base + (size_t)s * LW]; const float la = bflo(lw), u = bfhi(lw); h = __expf(la) * h + u; sla += la; }
	v_lshlrev_b32_e32 v143, 16, v29
	v_and_b32_e32 v145, 0xffff0000, v29
	v_mul_f32_e32 v144, 0x3fb8aa3b, v143
	v_exp_f32_e32 v144, v144
	v_add_f32_e32 v139, v139, v143
	v_fma_f32 v138, v144, v138, v145
	global_load_dword v93, v131, s[64:65]
	s_waitcnt vmcnt(63)
	v_lshlrev_b32_e32 v140, 16, v30
	v_and_b32_e32 v142, 0xffff0000, v30
	v_mul_f32_e32 v141, 0x3fb8aa3b, v140
	v_exp_f32_e32 v141, v141
	v_add_f32_e32 v139, v139, v140
	v_fma_f32 v138, v141, v138, v142
	global_load_dword v94, v132, s[64:65]
	s_waitcnt vmcnt(63)
	v_lshlrev_b32_e32 v143, 16, v31
	v_and_b32_e32 v145, 0xffff0000, v31
	v_mul_f32_e32 v144, 0x3fb8aa3b, v143
	v_exp_f32_e32 v144, v144
	v_add_f32_e32 v139, v139, v143
	v_fma_f32 v138, v144, v138, v145
	global_load_dword v95, v133, s[64:65]
	s_add_u32 s64, s64, 0x8000
	s_addc_u32 s65, s65, 0
	s_waitcnt vmcnt(63)
	v_lshlrev_b32_e32 v140, 16, v32
	v_and_b32_e32 v142, 0xffff0000, v32
	v_mul_f32_e32 v141, 0x3fb8aa3b, v140
	v_exp_f32_e32 v141, v141
	v_add_f32_e32 v139, v139, v140
	v_fma_f32 v138, v141, v138, v142
	global_load_dword v96, v130, s[64:65]
	s_waitcnt vmcnt(63)
	v_lshlrev_b32_e32 v143, 16, v33
	v_and_b32_e32 v145, 0xffff0000, v33
	v_mul_f32_e32 v144, 0x3fb8aa3b, v143
	v_exp_f32_e32 v144, v144
	v_add_f32_e32 v139, v139, v143
	v_fma_f32 v138, v144, v138, v145
	global_load_dword v97, v131, s[64:65]
	s_waitcnt vmcnt(63)
	v_lshlrev_b32_e32 v140, 16, v34
	v_and_b32_e32 v142, 0xffff0000, v34
	v_mul_f32_e32 v141, 0x3fb8aa3b, v140
	v_exp_f32_e32 v141, v141
	v_add_f32_e32 v139, v139, v140
	v_fma_f32 v138, v141, v138, v142
	global_load_dword v98, v132, s[64:65]
	s_waitcnt vmcnt(63)
	v_lshlrev_b32_e32 v143, 16, v35
	v_and_b32_e32 v145, 0xffff0000, v35
	v_mul_f32_e32 v144, 0x3fb8aa3b, v143
	v_exp_f32_e32 v144, v144
	v_add_f32_e32 v139, v139, v143
	v_fma_f32 v138, v144, v138, v145
	global_load_dword v99, v133, s[64:65]
	s_add_u32 s64, s64, 0x8000
	s_addc_u32 s65, s65, 0
	s_waitcnt vmcnt(63)
	v_lshlrev_b32_e32 v140, 16, v36
	v_and_b32_e32 v142, 0xffff0000, v36
	v_mul_f32_e32 v141, 0x3fb8aa3b, v140
	v_exp_f32_e32 v141, v141
	v_add_f32_e32 v139, v139, v140
	v_fma_f32 v138, v141, v138, v142
	global_load_dword v100, v130, s[64:65]
	s_waitcnt vmcnt(63)
	v_lshlrev_b32_e32 v143, 16, v37
	v_and_b32_e32 v145, 0xffff0000, v37
	v_mul_f32_e32 v144, 0x3fb8aa3b, v143
	v_exp_f32_e32 v144, v144
	v_add_f32_e32 v139, v139, v143
	v_fma_f32 v138, v144, v138, v145
	global_load_dword v101, v131, s[64:65]
	s_waitcnt vmcnt(63)
	v_lshlrev_b32_e32 v140, 16, v38
	v_and_b32_e32 v142, 0xffff0000, v38
	v_mul_f32_e32 v141, 0x3fb8aa3b, v140
	v_exp_f32_e32 v141, v141
	v_add_f32_e32 v139, v139, v140
	v_fma_f32 v138, v141, v138, v142
	global_load_dword v102, v132, s[64:65]
	s_waitcnt vmcnt(63)
	v_lshlrev_b32_e32 v143, 16, v39
	v_and_b32_e32 v145, 0xffff0000, v39
	v_mul_f32_e32 v144, 0x3fb8aa3b, v143
	v_exp_f32_e32 v144, v144
	v_add_f32_e32 v139, v139, v143
	v_fma_f32 v138, v144, v138, v145
	global_load_dword v103, v133, s[64:65]
	s_add_u32 s64, s64, 0x8000
	s_addc_u32 s65, s65, 0
	s_waitcnt vmcnt(63)
	v_lshlrev_b32_e32 v140, 16, v40
	v_and_b32_e32 v142, 0xffff0000, v40
	v_mul_f32_e32 v141, 0x3fb8aa3b, v140
	v_exp_f32_e32 v141, v141
	v_add_f32_e32 v139, v139, v140
	v_fma_f32 v138, v141, v138, v142
	global_load_dword v104, v130, s[64:65]
	s_waitcnt vmcnt(63)
	v_lshlrev_b32_e32 v143, 16, v41
	v_and_b32_e32 v145, 0xffff0000, v41
	v_mul_f32_e32 v144, 0x3fb8aa3b, v143
	v_exp_f32_e32 v144, v144
	v_add_f32_e32 v139, v139, v143
	v_fma_f32 v138, v144, v138, v145
	global_load_dword v105, v131, s[64:65]
	s_waitcnt vmcnt(63)
	v_lshlrev_b32_e32 v140, 16, v42
	v_and_b32_e32 v142, 0xffff0000, v42
	v_mul_f32_e32 v141, 0x3fb8aa3b, v140
	v_exp_f32_e32 v141, v141
	v_add_f32_e32 v139, v139, v140
	v_fma_f32 v138, v141, v138, v142
	global_load_dword v106, v132, s[64:65]
	s_waitcnt vmcnt(63)
	v_lshlrev_b32_e32 v143, 16, v43
	v_and_b32_e32 v145, 0xffff0000, v43
	v_mul_f32_e32 v144, 0x3fb8aa3b, v143
	v_exp_f32_e32 v144, v144
	v_add_f32_e32 v139, v139, v143
	v_fma_f32 v138, v144, v138, v145
	global_load_dword v107, v133, s[64:65]
	s_add_u32 s64, s64, 0x8000
	s_addc_u32 s65, s65, 0
	s_waitcnt vmcnt(63)
	v_lshlrev_b32_e32 v140, 16, v44
	v_and_b32_e32 v142, 0xffff0000, v44
	v_mul_f32_e32 v141, 0x3fb8aa3b, v140
	v_exp_f32_e32 v141, v141
	v_add_f32_e32 v139, v139, v140
	v_fma_f32 v138, v141, v138, v142
	global_load_dword v108, v130, s[64:65]
	s_waitcnt vmcnt(63)
	v_lshlrev_b32_e32 v143, 16, v45
	v_and_b32_e32 v145, 0xffff0000, v45
	v_mul_f32_e32 v144, 0x3fb8aa3b, v143
	v_exp_f32_e32 v144, v144
	v_add_f32_e32 v139, v139, v143
	v_fma_f32 v138, v144, v138, v145
	global_load_dword v109, v131, s[64:65]
	s_waitcnt vmcnt(63)
	v_lshlrev_b32_e32 v140, 16, v46
	v_and_b32_e32 v142, 0xffff0000, v46
	v_mul_f32_e32 v141, 0x3fb8aa3b, v140
	v_exp_f32_e32 v141, v141
	v_add_f32_e32 v139, v139, v140
	v_fma_f32 v138, v141, v138, v142
	global_load_dword v110, v132, s[64:65]
	s_waitcnt vmcnt(63)
	v_lshlrev_b32_e32 v143, 16, v47
	v_and_b32_e32 v145, 0xffff0000, v47
	v_mul_f32_e32 v144, 0x3fb8aa3b, v143
	v_exp_f32_e32 v144, v144
	v_add_f32_e32 v139, v139, v143
	v_fma_f32 v138, v144, v138, v145
	global_load_dword v111, v133, s[64:65]
	s_add_u32 s64, s64, 0x8000
	s_addc_u32 s65, s65, 0
	s_waitcnt vmcnt(63)
	v_lshlrev_b32_e32 v140, 16, v48
	v_and_b32_e32 v142, 0xffff0000, v48
	v_mul_f32_e32 v141, 0x3fb8aa3b, v140
	v_exp_f32_e32 v141, v141
	v_add_f32_e32 v139, v139, v140
	v_fma_f32 v138, v141, v138, v142
	global_load_dword v112, v130, s[64:65]
	s_waitcnt vmcnt(63)
	v_lshlrev_b32_e32 v143, 16, v49
	v_and_b32_e32 v145, 0xffff0000, v49
	v_mul_f32_e32 v144, 0x3fb8aa3b, v143
	v_exp_f32_e32 v144, v144
	v_add_f32_e32 v139, v139, v143
	v_fma_f32 v138, v144, v138, v145
	global_load_dword v113, v131, s[64:65]
	s_waitcnt vmcnt(63)
; __device__ __forceinline__ float bflo(unsigned w) { return __uint_as_float(w << 16); }
; __device__ __forceinline__ float bfhi(unsigned w) { return __uint_as_float(w & 0xffff0000u); }
; __device__ __forceinline__ void phase_scan(const Params& p, LAS unsigned char* lds) {
;     ...
;         float h = 0.f, sla = 0.f;
; #pragma unroll 8
;         for (int s = 0; s < 128; ++s) { const unsigned lw = LU[base + (size_t)s * LW]; const float la = bflo(lw), u = bfhi(lw); h = __expf(la) * h + u; sla += la; }
	v_lshlrev_b32_e32 v140, 16, v50
	v_and_b32_e32 v142, 0xffff0000, v50
	v_mul_f32_e32 v141, 0x3fb8aa3b, v140
	v_exp_f32_e32 v141, v141
	v_add_f32_e32 v139, v139, v140
	v_fma_f32 v138, v141, v138, v142
	global_load_dword v114, v132, s[64:65]
	s_waitcnt vmcnt(63)
	v_lshlrev_b32_e32 v143, 16, v51
	v_and_b32_e32 v145, 0xffff0000, v51
	v_mul_f32_e32 v144, 0x3fb8aa3b, v143
	v_exp_f32_e32 v144, v144
	v_add_f32_e32 v139, v139, v143
	v_fma_f32 v138, v144, v138, v145
	global_load_dword v115, v133, s[64:65]
	s_add_u32 s64, s64, 0x8000
	s_addc_u32 s65, s65, 0
	s_waitcnt vmcnt(63)
	v_lshlrev_b32_e32 v140, 16, v52
	v_and_b32_e32 v142, 0xffff0000, v52
	v_mul_f32_e32 v141, 0x3fb8aa3b, v140
	v_exp_f32_e32 v141, v141
	v_add_f32_e32 v139, v139, v140
	v_fma_f32 v138, v141, v138, v142
	global_load_dword v116, v130, s[64:65]
	s_waitcnt vmcnt(63)
	v_lshlrev_b32_e32 v143, 16, v53
	v_and_b32_e32 v145, 0xffff0000, v53
	v_mul_f32_e32 v144, 0x3fb8aa3b, v143
	v_exp_f32_e32 v144, v144
	v_add_f32_e32 v139, v139, v143
	v_fma_f32 v138, v144, v138, v145
	global_load_dword v117, v131, s[64:65]
	s_waitcnt vmcnt(63)
	v_lshlrev_b32_e32 v140, 16, v54
	v_and_b32_e32 v142, 0xffff0000, v54
	v_mul_f32_e32 v141, 0x3fb8aa3b, v140
	v_exp_f32_e32 v141, v141
	v_add_f32_e32 v139, v139, v140
	v_fma_f32 v138, v141, v138, v142
	global_load_dword v118, v132, s[64:65]
	s_waitcnt vmcnt(63)
	v_lshlrev_b32_e32 v143, 16, v55
	v_and_b32_e32 v145, 0xffff0000, v55
	v_mul_f32_e32 v144, 0x3fb8aa3b, v143
	v_exp_f32_e32 v144, v144
	v_add_f32_e32 v139, v139, v143
	v_fma_f32 v138, v144, v138, v145
	global_load_dword v119, v133, s[64:65]
	s_add_u32 s64, s64, 0x8000
	s_addc_u32 s65, s65, 0
	s_waitcnt vmcnt(63)
	v_lshlrev_b32_e32 v140, 16, v56
	v_and_b32_e32 v142, 0xffff0000, v56
	v_mul_f32_e32 v141, 0x3fb8aa3b, v140
	v_exp_f32_e32 v141, v141
	v_add_f32_e32 v139, v139, v140
	v_fma_f32 v138, v141, v138, v142
	global_load_dword v120, v130, s[64:65]
	s_waitcnt vmcnt(63)
	v_lshlrev_b32_e32 v143, 16, v57
	v_and_b32_e32 v145, 0xffff0000, v57
	v_mul_f32_e32 v144, 0x3fb8aa3b, v143
	v_exp_f32_e32 v144, v144
	v_add_f32_e32 v139, v139, v143
	v_fma_f32 v138, v144, v138, v145
	global_load_dword v121, v131, s[64:65]
	s_waitcnt vmcnt(63)
	v_lshlrev_b32_e32 v140, 16, v58
	v_and_b32_e32 v142, 0xffff0000, v58
	v_mul_f32_e32 v141, 0x3fb8aa3b, v140
	v_exp_f32_e32 v141, v141
	v_add_f32_e32 v139, v139, v140
	v_fma_f32 v138, v141, v138, v142
	global_load_dword v122, v132, s[64:65]
	s_waitcnt vmcnt(63)
	v_lshlrev_b32_e32 v143, 16, v59
	v_and_b32_e32 v145, 0xffff0000, v59
	v_mul_f32_e32 v144, 0x3fb8aa3b, v143
	v_exp_f32_e32 v144, v144
	v_add_f32_e32 v139, v139, v143
	v_fma_f32 v138, v144, v138, v145
	global_load_dword v123, v133, s[64:65]
	s_add_u32 s64, s64, 0x8000
	s_addc_u32 s65, s65, 0
	s_waitcnt vmcnt(63)
	v_lshlrev_b32_e32 v140, 16, v60
	v_and_b32_e32 v142, 0xffff0000, v60
	v_mul_f32_e32 v141, 0x3fb8aa3b, v140
	v_exp_f32_e32 v141, v141
	v_add_f32_e32 v139, v139, v140
	v_fma_f32 v138, v141, v138, v142
	global_load_dword v124, v130, s[64:65]
	s_waitcnt vmcnt(63)
	v_lshlrev_b32_e32 v143, 16, v61
	v_and_b32_e32 v145, 0xffff0000, v61
	v_mul_f32_e32 v144, 0x3fb8aa3b, v143
	v_exp_f32_e32 v144, v144
	v_add_f32_e32 v139, v139, v143
	v_fma_f32 v138, v144, v138, v145
	global_load_dword v125, v131, s[64:65]
	s_waitcnt vmcnt(63)
	v_lshlrev_b32_e32 v140, 16, v62
	v_and_b32_e32 v142, 0xffff0000, v62
	v_mul_f32_e32 v141, 0x3fb8aa3b, v140
	v_exp_f32_e32 v141, v141
	v_add_f32_e32 v139, v139, v140
	v_fma_f32 v138, v141, v138, v142
	global_load_dword v126, v132, s[64:65]
	s_waitcnt vmcnt(63)
	v_lshlrev_b32_e32 v143, 16, v63
	v_and_b32_e32 v145, 0xffff0000, v63
	v_mul_f32_e32 v144, 0x3fb8aa3b, v143
	v_exp_f32_e32 v144, v144
	v_add_f32_e32 v139, v139, v143
	v_fma_f32 v138, v144, v138, v145
	global_load_dword v127, v133, s[64:65]
	s_waitcnt vmcnt(63)
	v_lshlrev_b32_e32 v140, 16, v64
	v_and_b32_e32 v142, 0xffff0000, v64
	v_mul_f32_e32 v141, 0x3fb8aa3b, v140
	v_exp_f32_e32 v141, v141
	v_add_f32_e32 v139, v139, v140
	v_fma_f32 v138, v141, v138, v142
	s_waitcnt vmcnt(62)
	v_lshlrev_b32_e32 v143, 16, v65
	v_and_b32_e32 v145, 0xffff0000, v65
	v_mul_f32_e32 v144, 0x3fb8aa3b, v143
	v_exp_f32_e32 v144, v144
	v_add_f32_e32 v139, v139, v143
	v_fma_f32 v138, v144, v138, v145
	s_waitcnt vmcnt(61)
	v_lshlrev_b32_e32 v140, 16, v66
	v_and_b32_e32 v142, 0xffff0000, v66
	v_mul_f32_e32 v141, 0x3fb8aa3b, v140
	v_exp_f32_e32 v141, v141
	v_add_f32_e32 v139, v139, v140
	v_fma_f32 v138, v141, v138, v142
	s_waitcnt vmcnt(60)
	v_lshlrev_b32_e32 v143, 16, v67
	v_and_b32_e32 v145, 0xffff0000, v67
	v_mul_f32_e32 v144, 0x3fb8aa3b, v143
	v_exp_f32_e32 v144, v144
	v_add_f32_e32 v139, v139, v143
	v_fma_f32 v138, v144, v138, v145
	s_waitcnt vmcnt(59)
	v_lshlrev_b32_e32 v140, 16, v68
	v_and_b32_e32 v142, 0xffff0000, v68
	v_mul_f32_e32 v141, 0x3fb8aa3b, v140
	v_exp_f32_e32 v141, v141
	v_add_f32_e32 v139, v139, v140
	v_fma_f32 v138, v141, v138, v142
	s_waitcnt vmcnt(58)
	v_lshlrev_b32_e32 v143, 16, v69
	v_and_b32_e32 v145, 0xffff0000, v69
	v_mul_f32_e32 v144, 0x3fb8aa3b, v143
	v_exp_f32_e32 v144, v144
	v_add_f32_e32 v139, v139, v143
	v_fma_f32 v138, v144, v138, v145
	s_waitcnt vmcnt(57)
	v_lshlrev_b32_e32 v140, 16, v70
	v_and_b32_e32 v142, 0xffff0000, v70
	v_mul_f32_e32 v141, 0x3fb8aa3b, v140
	v_exp_f32_e32 v141, v141
	v_add_f32_e32 v139, v139, v140
	v_fma_f32 v138, v141, v138, v142
	s_waitcnt vmcnt(56)
	v_lshlrev_b32_e32 v143, 16, v71
	v_and_b32_e32 v145, 0xffff0000, v71
	v_mul_f32_e32 v144, 0x3fb8aa3b, v143
	v_exp_f32_e32 v144, v144
	v_add_f32_e32 v139, v139, v143
	v_fma_f32 v138, v144, v138, v145
	s_waitcnt vmcnt(55)
; __device__ __forceinline__ float bflo(unsigned w) { return __uint_as_float(w << 16); }
; __device__ __forceinline__ float bfhi(unsigned w) { return __uint_as_float(w & 0xffff0000u); }
; __device__ __forceinline__ void phase_scan(const Params& p, LAS unsigned char* lds) {
;     ...
;         float h = 0.f, sla = 0.f;
; #pragma unroll 8
;         for (int s = 0; s < 128; ++s) { const unsigned lw = LU[base + (size_t)s * LW]; const float la = bflo(lw), u = bfhi(lw); h = __expf(la) * h + u; sla += la; }
	v_lshlrev_b32_e32 v140, 16, v72
	v_and_b32_e32 v142, 0xffff0000, v72
	v_mul_f32_e32 v141, 0x3fb8aa3b, v140
	v_exp_f32_e32 v141, v141
	v_add_f32_e32 v139, v139, v140
	v_fma_f32 v138, v141, v138, v142
	s_waitcnt vmcnt(54)
	v_lshlrev_b32_e32 v143, 16, v73
	v_and_b32_e32 v145, 0xffff0000, v73
	v_mul_f32_e32 v144, 0x3fb8aa3b, v143
	v_exp_f32_e32 v144, v144
	v_add_f32_e32 v139, v139, v143
	v_fma_f32 v138, v144, v138, v145
	s_waitcnt vmcnt(53)
	v_lshlrev_b32_e32 v140, 16, v74
	v_and_b32_e32 v142, 0xffff0000, v74
	v_mul_f32_e32 v141, 0x3fb8aa3b, v140
	v_exp_f32_e32 v141, v141
	v_add_f32_e32 v139, v139, v140
	v_fma_f32 v138, v141, v138, v142
	s_waitcnt vmcnt(52)
	v_lshlrev_b32_e32 v143, 16, v75
	v_and_b32_e32 v145, 0xffff0000, v75
	v_mul_f32_e32 v144, 0x3fb8aa3b, v143
	v_exp_f32_e32 v144, v144
	v_add_f32_e32 v139, v139, v143
	v_fma_f32 v138, v144, v138, v145
	s_waitcnt vmcnt(51)
	v_lshlrev_b32_e32 v140, 16, v76
	v_and_b32_e32 v142, 0xffff0000, v76
	v_mul_f32_e32 v141, 0x3fb8aa3b, v140
	v_exp_f32_e32 v141, v141
	v_add_f32_e32 v139, v139, v140
	v_fma_f32 v138, v141, v138, v142
	s_waitcnt vmcnt(50)
	v_lshlrev_b32_e32 v143, 16, v77
	v_and_b32_e32 v145, 0xffff0000, v77
	v_mul_f32_e32 v144, 0x3fb8aa3b, v143
	v_exp_f32_e32 v144, v144
	v_add_f32_e32 v139, v139, v143
	v_fma_f32 v138, v144, v138, v145
	s_waitcnt vmcnt(49)
	v_lshlrev_b32_e32 v140, 16, v78
	v_and_b32_e32 v142, 0xffff0000, v78
	v_mul_f32_e32 v141, 0x3fb8aa3b, v140
	v_exp_f32_e32 v141, v141
	v_add_f32_e32 v139, v139, v140
	v_fma_f32 v138, v141, v138, v142
	s_waitcnt vmcnt(48)
	v_lshlrev_b32_e32 v143, 16, v79
	v_and_b32_e32 v145, 0xffff0000, v79
	v_mul_f32_e32 v144, 0x3fb8aa3b, v143
	v_exp_f32_e32 v144, v144
	v_add_f32_e32 v139, v139, v143
	v_fma_f32 v138, v144, v138, v145
	s_waitcnt vmcnt(47)
	v_lshlrev_b32_e32 v140, 16, v80
	v_and_b32_e32 v142, 0xffff0000, v80
	v_mul_f32_e32 v141, 0x3fb8aa3b, v140
	v_exp_f32_e32 v141, v141
	v_add_f32_e32 v139, v139, v140
	v_fma_f32 v138, v141, v138, v142
	s_waitcnt vmcnt(46)
	v_lshlrev_b32_e32 v143, 16, v81
	v_and_b32_e32 v145, 0xffff0000, v81
	v_mul_f32_e32 v144, 0x3fb8aa3b, v143
	v_exp_f32_e32 v144, v144
	v_add_f32_e32 v139, v139, v143
	v_fma_f32 v138, v144, v138, v145
	s_waitcnt vmcnt(45)
	v_lshlrev_b32_e32 v140, 16, v82
	v_and_b32_e32 v142, 0xffff0000, v82
	v_mul_f32_e32 v141, 0x3fb8aa3b, v140
	v_exp_f32_e32 v141, v141
	v_add_f32_e32 v139, v139, v140
	v_fma_f32 v138, v141, v138, v142
	s_waitcnt vmcnt(44)
	v_lshlrev_b32_e32 v143, 16, v83
	v_and_b32_e32 v145, 0xffff0000, v83
	v_mul_f32_e32 v144, 0x3fb8aa3b, v143
	v_exp_f32_e32 v144, v144
	v_add_f32_e32 v139, v139, v143
	v_fma_f32 v138, v144, v138, v145
	s_waitcnt vmcnt(43)
	v_lshlrev_b32_e32 v140, 16, v84
	v_and_b32_e32 v142, 0xffff0000, v84
	v_mul_f32_e32 v141, 0x3fb8aa3b, v140
	v_exp_f32_e32 v141, v141
	v_add_f32_e32 v139, v139, v140
	v_fma_f32 v138, v141, v138, v142
	s_waitcnt vmcnt(42)
	v_lshlrev_b32_e32 v143, 16, v85
	v_and_b32_e32 v145, 0xffff0000, v85
	v_mul_f32_e32 v144, 0x3fb8aa3b, v143
	v_exp_f32_e32 v144, v144
	v_add_f32_e32 v139, v139, v143
	v_fma_f32 v138, v144, v138, v145
	s_waitcnt vmcnt(41)
	v_lshlrev_b32_e32 v140, 16, v86
	v_and_b32_e32 v142, 0xffff0000, v86
	v_mul_f32_e32 v141, 0x3fb8aa3b, v140
	v_exp_f32_e32 v141, v141
	v_add_f32_e32 v139, v139, v140
	v_fma_f32 v138, v141, v138, v142
	s_waitcnt vmcnt(40)
	v_lshlrev_b32_e32 v143, 16, v87
	v_and_b32_e32 v145, 0xffff0000, v87
	v_mul_f32_e32 v144, 0x3fb8aa3b, v143
	v_exp_f32_e32 v144, v144
	v_add_f32_e32 v139, v139, v143
	v_fma_f32 v138, v144, v138, v145
	s_waitcnt vmcnt(39)
	v_lshlrev_b32_e32 v140, 16, v88
	v_and_b32_e32 v142, 0xffff0000, v88
	v_mul_f32_e32 v141, 0x3fb8aa3b, v140
	v_exp_f32_e32 v141, v141
	v_add_f32_e32 v139, v139, v140
	v_fma_f32 v138, v141, v138, v142
	s_waitcnt vmcnt(38)
	v_lshlrev_b32_e32 v143, 16, v89
	v_and_b32_e32 v145, 0xffff0000, v89
	v_mul_f32_e32 v144, 0x3fb8aa3b, v143
	v_exp_f32_e32 v144, v144
	v_add_f32_e32 v139, v139, v143
	v_fma_f32 v138, v144, v138, v145
	s_waitcnt vmcnt(37)
	v_lshlrev_b32_e32 v140, 16, v90
	v_and_b32_e32 v142, 0xffff0000, v90
	v_mul_f32_e32 v141, 0x3fb8aa3b, v140
	v_exp_f32_e32 v141, v141
	v_add_f32_e32 v139, v139, v140
	v_fma_f32 v138, v141, v138, v142
	s_waitcnt vmcnt(36)
	v_lshlrev_b32_e32 v143, 16, v91
	v_and_b32_e32 v145, 0xffff0000, v91
	v_mul_f32_e32 v144, 0x3fb8aa3b, v143
	v_exp_f32_e32 v144, v144
	v_add_f32_e32 v139, v139, v143
	v_fma_f32 v138, v144, v138, v145
	s_waitcnt vmcnt(35)
	v_lshlrev_b32_e32 v140, 16, v92
	v_and_b32_e32 v142, 0xffff0000, v92
	v_mul_f32_e32 v141, 0x3fb8aa3b, v140
	v_exp_f32_e32 v141, v141
	v_add_f32_e32 v139, v139, v140
	v_fma_f32 v138, v141, v138, v142
	s_waitcnt vmcnt(34)
	v_lshlrev_b32_e32 v143, 16, v93
	v_and_b32_e32 v145, 0xffff0000, v93
	v_mul_f32_e32 v144, 0x3fb8aa3b, v143
	v_exp_f32_e32 v144, v144
	v_add_f32_e32 v139, v139, v143
	v_fma_f32 v138, v144, v138, v145
	s_waitcnt vmcnt(33)
	v_lshlrev_b32_e32 v140, 16, v94
	v_and_b32_e32 v142, 0xffff0000, v94
	v_mul_f32_e32 v141, 0x3fb8aa3b, v140
	v_exp_f32_e32 v141, v141
	v_add_f32_e32 v139, v139, v140
	v_fma_f32 v138, v141, v138, v142
	s_waitcnt vmcnt(32)
	v_lshlrev_b32_e32 v143, 16, v95
	v_and_b32_e32 v145, 0xffff0000, v95
	v_mul_f32_e32 v144, 0x3fb8aa3b, v143
	v_exp_f32_e32 v144, v144
	v_add_f32_e32 v139, v139, v143
	v_fma_f32 v138, v144, v138, v145
	s_waitcnt vmcnt(31)
	v_lshlrev_b32_e32 v140, 16, v96
	v_and_b32_e32 v142, 0xffff0000, v96
	v_mul_f32_e32 v141, 0x3fb8aa3b, v140
	v_exp_f32_e32 v141, v141
	v_add_f32_e32 v139, v139, v140
	v_fma_f32 v138, v141, v138, v142
	s_waitcnt vmcnt(30)
	v_lshlrev_b32_e32 v143, 16, v97
	v_and_b32_e32 v145, 0xffff0000, v97
	v_mul_f32_e32 v144, 0x3fb8aa3b, v143
	v_exp_f32_e32 v144, v144
	v_add_f32_e32 v139, v139, v143
	v_fma_f32 v138, v144, v138, v145
	s_waitcnt vmcnt(29)
; __device__ __forceinline__ float bflo(unsigned w) { return __uint_as_float(w << 16); }
; __device__ __forceinline__ float bfhi(unsigned w) { return __uint_as_float(w & 0xffff0000u); }
; __device__ __forceinline__ void phase_scan(const Params& p, LAS unsigned char* lds) {
;     ...
;         for (int s = 0; s < 128; ++s) { const unsigned lw = LU[base + (size_t)s * LW]; const float la = bflo(lw), u = bfhi(lw); h = __expf(la) * h + u; sla += la; }
;         sA[chunk * 32 + c32] = __expf(sla); sH[chunk * 32 + c32] = h;
;         __syncthreads();
	v_lshlrev_b32_e32 v140, 16, v98
	v_and_b32_e32 v142, 0xffff0000, v98
	v_mul_f32_e32 v141, 0x3fb8aa3b, v140
	v_exp_f32_e32 v141, v141
	v_add_f32_e32 v139, v139, v140
	v_fma_f32 v138, v141, v138, v142
	s_waitcnt vmcnt(28)
	v_lshlrev_b32_e32 v143, 16, v99
	v_and_b32_e32 v145, 0xffff0000, v99
	v_mul_f32_e32 v144, 0x3fb8aa3b, v143
	v_exp_f32_e32 v144, v144
	v_add_f32_e32 v139, v139, v143
	v_fma_f32 v138, v144, v138, v145
	s_waitcnt vmcnt(27)
	v_lshlrev_b32_e32 v140, 16, v100
	v_and_b32_e32 v142, 0xffff0000, v100
	v_mul_f32_e32 v141, 0x3fb8aa3b, v140
	v_exp_f32_e32 v141, v141
	v_add_f32_e32 v139, v139, v140
	v_fma_f32 v138, v141, v138, v142
	s_waitcnt vmcnt(26)
	v_lshlrev_b32_e32 v143, 16, v101
	v_and_b32_e32 v145, 0xffff0000, v101
	v_mul_f32_e32 v144, 0x3fb8aa3b, v143
	v_exp_f32_e32 v144, v144
	v_add_f32_e32 v139, v139, v143
	v_fma_f32 v138, v144, v138, v145
	s_waitcnt vmcnt(25)
	v_lshlrev_b32_e32 v140, 16, v102
	v_and_b32_e32 v142, 0xffff0000, v102
	v_mul_f32_e32 v141, 0x3fb8aa3b, v140
	v_exp_f32_e32 v141, v141
	v_add_f32_e32 v139, v139, v140
	v_fma_f32 v138, v141, v138, v142
	s_waitcnt vmcnt(24)
	v_lshlrev_b32_e32 v143, 16, v103
	v_and_b32_e32 v145, 0xffff0000, v103
	v_mul_f32_e32 v144, 0x3fb8aa3b, v143
	v_exp_f32_e32 v144, v144
	v_add_f32_e32 v139, v139, v143
	v_fma_f32 v138, v144, v138, v145
	s_waitcnt vmcnt(23)
	v_lshlrev_b32_e32 v140, 16, v104
	v_and_b32_e32 v142, 0xffff0000, v104
	v_mul_f32_e32 v141, 0x3fb8aa3b, v140
	v_exp_f32_e32 v141, v141
	v_add_f32_e32 v139, v139, v140
	v_fma_f32 v138, v141, v138, v142
	s_waitcnt vmcnt(22)
	v_lshlrev_b32_e32 v143, 16, v105
	v_and_b32_e32 v145, 0xffff0000, v105
	v_mul_f32_e32 v144, 0x3fb8aa3b, v143
	v_exp_f32_e32 v144, v144
	v_add_f32_e32 v139, v139, v143
	v_fma_f32 v138, v144, v138, v145
	s_waitcnt vmcnt(21)
	v_lshlrev_b32_e32 v140, 16, v106
	v_and_b32_e32 v142, 0xffff0000, v106
	v_mul_f32_e32 v141, 0x3fb8aa3b, v140
	v_exp_f32_e32 v141, v141
	v_add_f32_e32 v139, v139, v140
	v_fma_f32 v138, v141, v138, v142
	s_waitcnt vmcnt(20)
	v_lshlrev_b32_e32 v143, 16, v107
	v_and_b32_e32 v145, 0xffff0000, v107
	v_mul_f32_e32 v144, 0x3fb8aa3b, v143
	v_exp_f32_e32 v144, v144
	v_add_f32_e32 v139, v139, v143
	v_fma_f32 v138, v144, v138, v145
	s_waitcnt vmcnt(19)
	v_lshlrev_b32_e32 v140, 16, v108
	v_and_b32_e32 v142, 0xffff0000, v108
	v_mul_f32_e32 v141, 0x3fb8aa3b, v140
	v_exp_f32_e32 v141, v141
	v_add_f32_e32 v139, v139, v140
	v_fma_f32 v138, v141, v138, v142
	s_waitcnt vmcnt(18)
	v_lshlrev_b32_e32 v143, 16, v109
	v_and_b32_e32 v145, 0xffff0000, v109
	v_mul_f32_e32 v144, 0x3fb8aa3b, v143
	v_exp_f32_e32 v144, v144
	v_add_f32_e32 v139, v139, v143
	v_fma_f32 v138, v144, v138, v145
	s_waitcnt vmcnt(17)
	v_lshlrev_b32_e32 v140, 16, v110
	v_and_b32_e32 v142, 0xffff0000, v110
	v_mul_f32_e32 v141, 0x3fb8aa3b, v140
	v_exp_f32_e32 v141, v141
	v_add_f32_e32 v139, v139, v140
	v_fma_f32 v138, v141, v138, v142
	s_waitcnt vmcnt(16)
	v_lshlrev_b32_e32 v143, 16, v111
	v_and_b32_e32 v145, 0xffff0000, v111
	v_mul_f32_e32 v144, 0x3fb8aa3b, v143
	v_exp_f32_e32 v144, v144
	v_add_f32_e32 v139, v139, v143
	v_fma_f32 v138, v144, v138, v145
	s_waitcnt vmcnt(15)
	v_lshlrev_b32_e32 v140, 16, v112
	v_and_b32_e32 v142, 0xffff0000, v112
	v_mul_f32_e32 v141, 0x3fb8aa3b, v140
	v_exp_f32_e32 v141, v141
	v_add_f32_e32 v139, v139, v140
	v_fma_f32 v138, v141, v138, v142
	s_waitcnt vmcnt(14)
	v_lshlrev_b32_e32 v143, 16, v113
	v_and_b32_e32 v145, 0xffff0000, v113
	v_mul_f32_e32 v144, 0x3fb8aa3b, v143
	v_exp_f32_e32 v144, v144
	v_add_f32_e32 v139, v139, v143
	v_fma_f32 v138, v144, v138, v145
	s_waitcnt vmcnt(13)
	v_lshlrev_b32_e32 v140, 16, v114
	v_and_b32_e32 v142, 0xffff0000, v114
	v_mul_f32_e32 v141, 0x3fb8aa3b, v140
	v_exp_f32_e32 v141, v141
	v_add_f32_e32 v139, v139, v140
	v_fma_f32 v138, v141, v138, v142
	s_waitcnt vmcnt(12)
	v_lshlrev_b32_e32 v143, 16, v115
	v_and_b32_e32 v145, 0xffff0000, v115
	v_mul_f32_e32 v144, 0x3fb8aa3b, v143
	v_exp_f32_e32 v144, v144
	v_add_f32_e32 v139, v139, v143
	v_fma_f32 v138, v144, v138, v145
	s_waitcnt vmcnt(11)
	v_lshlrev_b32_e32 v140, 16, v116
	v_and_b32_e32 v142, 0xffff0000, v116
	v_mul_f32_e32 v141, 0x3fb8aa3b, v140
	v_exp_f32_e32 v141, v141
	v_add_f32_e32 v139, v139, v140
	v_fma_f32 v138, v141, v138, v142
	s_waitcnt vmcnt(10)
	v_lshlrev_b32_e32 v143, 16, v117
	v_and_b32_e32 v145, 0xffff0000, v117
	v_mul_f32_e32 v144, 0x3fb8aa3b, v143
	v_exp_f32_e32 v144, v144
	v_add_f32_e32 v139, v139, v143
	v_fma_f32 v138, v144, v138, v145
	s_waitcnt vmcnt(9)
	v_lshlrev_b32_e32 v140, 16, v118
	v_and_b32_e32 v142, 0xffff0000, v118
	v_mul_f32_e32 v141, 0x3fb8aa3b, v140
	v_exp_f32_e32 v141, v141
	v_add_f32_e32 v139, v139, v140
	v_fma_f32 v138, v141, v138, v142
	s_waitcnt vmcnt(8)
	v_lshlrev_b32_e32 v143, 16, v119
	v_and_b32_e32 v145, 0xffff0000, v119
	v_mul_f32_e32 v144, 0x3fb8aa3b, v143
	v_exp_f32_e32 v144, v144
	v_add_f32_e32 v139, v139, v143
	v_fma_f32 v138, v144, v138, v145
	s_waitcnt vmcnt(7)
	v_lshlrev_b32_e32 v140, 16, v120
	v_and_b32_e32 v142, 0xffff0000, v120
	v_mul_f32_e32 v141, 0x3fb8aa3b, v140
	v_exp_f32_e32 v141, v141
	v_add_f32_e32 v139, v139, v140
	v_fma_f32 v138, v141, v138, v142
	s_waitcnt vmcnt(6)
	v_lshlrev_b32_e32 v143, 16, v121
	v_and_b32_e32 v145, 0xffff0000, v121
	v_mul_f32_e32 v144, 0x3fb8aa3b, v143
	v_exp_f32_e32 v144, v144
	v_add_f32_e32 v139, v139, v143
	v_fma_f32 v138, v144, v138, v145
	s_waitcnt vmcnt(5)
	v_lshlrev_b32_e32 v140, 16, v122
	v_and_b32_e32 v142, 0xffff0000, v122
	v_mul_f32_e32 v141, 0x3fb8aa3b, v140
	v_exp_f32_e32 v141, v141
	v_add_f32_e32 v139, v139, v140
	v_fma_f32 v138, v141, v138, v142
	s_waitcnt vmcnt(4)
	v_lshlrev_b32_e32 v143, 16, v123
	v_and_b32_e32 v145, 0xffff0000, v123
	v_mul_f32_e32 v144, 0x3fb8aa3b, v143
	v_exp_f32_e32 v144, v144
	v_add_f32_e32 v139, v139, v143
	v_fma_f32 v138, v144, v138, v145
	s_waitcnt vmcnt(3)
	v_lshlrev_b32_e32 v140, 16, v124
	v_and_b32_e32 v142, 0xffff0000, v124
	v_mul_f32_e32 v141, 0x3fb8aa3b, v140
	v_exp_f32_e32 v141, v141
	v_add_f32_e32 v139, v139, v140
	v_fma_f32 v138, v141, v138, v142
	s_waitcnt vmcnt(2)
	v_lshlrev_b32_e32 v143, 16, v125
	v_and_b32_e32 v145, 0xffff0000, v125
	v_mul_f32_e32 v144, 0x3fb8aa3b, v143
	v_exp_f32_e32 v144, v144
	v_add_f32_e32 v139, v139, v143
	v_fma_f32 v138, v144, v138, v145
	s_waitcnt vmcnt(1)
	v_lshlrev_b32_e32 v140, 16, v126
	v_and_b32_e32 v142, 0xffff0000, v126
	v_mul_f32_e32 v141, 0x3fb8aa3b, v140
	v_exp_f32_e32 v141, v141
	v_add_f32_e32 v139, v139, v140
	v_fma_f32 v138, v141, v138, v142
	s_waitcnt vmcnt(0)
	v_lshlrev_b32_e32 v143, 16, v127
	v_and_b32_e32 v145, 0xffff0000, v127
	v_mul_f32_e32 v144, 0x3fb8aa3b, v143
	v_exp_f32_e32 v144, v144
	v_add_f32_e32 v139, v139, v143
	v_fma_f32 v138, v144, v138, v145
	v_mul_f32_e32 v140, 0x3fb8aa3b, v139
	v_exp_f32_e32 v140, v140
	s_nop 1
	ds_write_b32 v185, v140
	ds_write_b32 v185, v138 offset:2048
	s_waitcnt lgkmcnt(0)
	s_barrier
; __device__ __forceinline__ unsigned pk2(float lo, float hi) { unsigned r; asm("v_cvt_pk_bf16_f32 %0, %1, %2" : "=v"(r) : "v"(lo), "v"(hi)); return r; }
; __device__ __forceinline__ float bflo(unsigned w) { return __uint_as_float(w << 16); }
; __device__ __forceinline__ float bfhi(unsigned w) { return __uint_as_float(w & 0xffff0000u); }
; __device__ __forceinline__ void phase_scan(const Params& p, LAS unsigned char* lds) {
;     ...
;         __syncthreads();
;         float hin = 0.f;
;         for (int j = 0; j < chunk; ++j) hin = sA[j * 32 + c32] * hin + sH[j * 32 + c32];
;         h = hin;
; #pragma unroll 8
;         for (int s = 0; s < 128; ++s) { const unsigned lw = __builtin_nontemporal_load(LU + base + (size_t)s * LW); const float la = bflo(lw), u = bfhi(lw); h = __expf(la) * h + u;
;             YL[base + (size_t)s * LW] = (bf16_t)(pk2(h, h) & 0xffffu); }
	ds_read_b32 v150, v148 offset:0
	ds_read_b32 v165, v148 offset:2048
	ds_read_b32 v151, v148 offset:128
	ds_read_b32 v166, v148 offset:2176
	ds_read_b32 v152, v148 offset:256
	ds_read_b32 v167, v148 offset:2304
	ds_read_b32 v153, v148 offset:384
	ds_read_b32 v168, v148 offset:2432
	ds_read_b32 v154, v148 offset:512
	ds_read_b32 v169, v148 offset:2560
	ds_read_b32 v155, v148 offset:640
	ds_read_b32 v170, v148 offset:2688
	ds_read_b32 v156, v148 offset:768
	ds_read_b32 v171, v148 offset:2816
	ds_read_b32 v157, v148 offset:896
	ds_read_b32 v172, v148 offset:2944
	ds_read_b32 v158, v148 offset:1024
	ds_read_b32 v173, v148 offset:3072
	ds_read_b32 v159, v148 offset:1152
	ds_read_b32 v174, v148 offset:3200
	ds_read_b32 v160, v148 offset:1280
	ds_read_b32 v175, v148 offset:3328
	ds_read_b32 v161, v148 offset:1408
	ds_read_b32 v176, v148 offset:3456
	ds_read_b32 v162, v148 offset:1536
	ds_read_b32 v177, v148 offset:3584
	ds_read_b32 v163, v148 offset:1664
	ds_read_b32 v178, v148 offset:3712
	ds_read_b32 v164, v148 offset:1792
	ds_read_b32 v179, v148 offset:3840
	v_cmp_eq_u32_e64 s[4:5], 1, v128
	v_cmp_eq_u32_e64 s[6:7], 2, v128
	v_cmp_eq_u32_e64 s[8:9], 3, v128
	v_cmp_eq_u32_e64 s[10:11], 4, v128
	v_cmp_eq_u32_e64 s[12:13], 5, v128
	v_cmp_eq_u32_e64 s[14:15], 6, v128
	v_cmp_eq_u32_e64 s[16:17], 7, v128
	v_cmp_eq_u32_e64 s[18:19], 8, v128
	v_cmp_eq_u32_e64 s[20:21], 9, v128
	v_cmp_eq_u32_e64 s[22:23], 10, v128
	v_cmp_eq_u32_e64 s[24:25], 11, v128
	v_cmp_eq_u32_e64 s[26:27], 12, v128
	v_cmp_eq_u32_e64 s[28:29], 13, v128
	v_cmp_eq_u32_e64 s[30:31], 14, v128
	v_cmp_eq_u32_e64 s[58:59], 15, v128
	v_mov_b32_e32 v141, 0
	v_mov_b32_e32 v142, 0
	s_waitcnt lgkmcnt(15)
	v_fma_f32 v141, v150, v141, v165
	v_cndmask_b32_e64 v142, v142, v141, s[4:5]
	s_waitcnt lgkmcnt(15)
	v_fma_f32 v141, v151, v141, v166
	v_cndmask_b32_e64 v142, v142, v141, s[6:7]
	s_waitcnt lgkmcnt(15)
	v_fma_f32 v141, v152, v141, v167
	v_cndmask_b32_e64 v142, v142, v141, s[8:9]
	s_waitcnt lgkmcnt(15)
	v_fma_f32 v141, v153, v141, v168
	v_cndmask_b32_e64 v142, v142, v141, s[10:11]
	s_waitcnt lgkmcnt(15)
	v_fma_f32 v141, v154, v141, v169
	v_cndmask_b32_e64 v142, v142, v141, s[12:13]
	s_waitcnt lgkmcnt(15)
	v_fma_f32 v141, v155, v141, v170
	v_cndmask_b32_e64 v142, v142, v141, s[14:15]
	s_waitcnt lgkmcnt(15)
	v_fma_f32 v141, v156, v141, v171
	v_cndmask_b32_e64 v142, v142, v141, s[16:17]
	s_waitcnt lgkmcnt(14)
	v_fma_f32 v141, v157, v141, v172
	v_cndmask_b32_e64 v142, v142, v141, s[18:19]
	s_waitcnt lgkmcnt(12)
	v_fma_f32 v141, v158, v141, v173
	v_cndmask_b32_e64 v142, v142, v141, s[20:21]
	s_waitcnt lgkmcnt(10)
	v_fma_f32 v141, v159, v141, v174
	v_cndmask_b32_e64 v142, v142, v141, s[22:23]
	s_waitcnt lgkmcnt(8)
	v_fma_f32 v141, v160, v141, v175
	v_cndmask_b32_e64 v142, v142, v141, s[24:25]
	s_waitcnt lgkmcnt(6)
	v_fma_f32 v141, v161, v141, v176
	v_cndmask_b32_e64 v142, v142, v141, s[26:27]
	s_waitcnt lgkmcnt(4)
	v_fma_f32 v141, v162, v141, v177
	v_cndmask_b32_e64 v142, v142, v141, s[28:29]
	s_waitcnt lgkmcnt(2)
	v_fma_f32 v141, v163, v141, v178
	v_cndmask_b32_e64 v142, v142, v141, s[30:31]
	s_waitcnt lgkmcnt(0)
	v_fma_f32 v141, v164, v141, v179
	v_cndmask_b32_e64 v142, v142, v141, s[58:59]
	v_lshlrev_b32_e32 v140, 16, v0
	v_mul_f32_e32 v140, 0x3fb8aa3b, v140
	v_exp_f32_e32 v140, v140
	v_and_b32_e32 v0, 0xffff0000, v0
	v_fma_f32 v142, v140, v142, v0
	v_cvt_pk_bf16_f32 v0, v142, v142
	global_store_short v134, v0, s[66:67]
	v_lshlrev_b32_e32 v143, 16, v1
	v_mul_f32_e32 v143, 0x3fb8aa3b, v143
	v_exp_f32_e32 v143, v143
	v_and_b32_e32 v1, 0xffff0000, v1
	v_fma_f32 v142, v143, v142, v1
	v_cvt_pk_bf16_f32 v1, v142, v142
	global_store_short v135, v1, s[66:67]
	v_lshlrev_b32_e32 v140, 16, v2
	v_mul_f32_e32 v140, 0x3fb8aa3b, v140
	v_exp_f32_e32 v140, v140
	v_and_b32_e32 v2, 0xffff0000, v2
	v_fma_f32 v142, v140, v142, v2
	v_cvt_pk_bf16_f32 v2, v142, v142
	global_store_short v136, v2, s[66:67]
	v_lshlrev_b32_e32 v143, 16, v3
	v_mul_f32_e32 v143, 0x3fb8aa3b, v143
	v_exp_f32_e32 v143, v143
	v_and_b32_e32 v3, 0xffff0000, v3
	v_fma_f32 v142, v143, v142, v3
	v_cvt_pk_bf16_f32 v3, v142, v142
	global_store_short v137, v3, s[66:67]
	s_add_u32 s66, s66, 0x4000
	s_addc_u32 s67, s67, 0
	v_lshlrev_b32_e32 v140, 16, v4
	v_mul_f32_e32 v140, 0x3fb8aa3b, v140
	v_exp_f32_e32 v140, v140
	v_and_b32_e32 v4, 0xffff0000, v4
	v_fma_f32 v142, v140, v142, v4
	v_cvt_pk_bf16_f32 v4, v142, v142
	global_store_short v134, v4, s[66:67]
	v_lshlrev_b32_e32 v143, 16, v5
	v_mul_f32_e32 v143, 0x3fb8aa3b, v143
	v_exp_f32_e32 v143, v143
	v_and_b32_e32 v5, 0xffff0000, v5
	v_fma_f32 v142, v143, v142, v5
	v_cvt_pk_bf16_f32 v5, v142, v142
	global_store_short v135, v5, s[66:67]
	v_lshlrev_b32_e32 v140, 16, v6
	v_mul_f32_e32 v140, 0x3fb8aa3b, v140
	v_exp_f32_e32 v140, v140
	v_and_b32_e32 v6, 0xffff0000, v6
	v_fma_f32 v142, v140, v142, v6
	v_cvt_pk_bf16_f32 v6, v142, v142
	global_store_short v136, v6, s[66:67]
	v_lshlrev_b32_e32 v143, 16, v7
	v_mul_f32_e32 v143, 0x3fb8aa3b, v143
	v_exp_f32_e32 v143, v143
	v_and_b32_e32 v7, 0xffff0000, v7
	v_fma_f32 v142, v143, v142, v7
	v_cvt_pk_bf16_f32 v7, v142, v142
	global_store_short v137, v7, s[66:67]
	s_add_u32 s66, s66, 0x4000
	s_addc_u32 s67, s67, 0
	v_lshlrev_b32_e32 v140, 16, v8
	v_mul_f32_e32 v140, 0x3fb8aa3b, v140
	v_exp_f32_e32 v140, v140
	v_and_b32_e32 v8, 0xffff0000, v8
	v_fma_f32 v142, v140, v142, v8
	v_cvt_pk_bf16_f32 v8, v142, v142
	global_store_short v134, v8, s[66:67]
	v_lshlrev_b32_e32 v143, 16, v9
	v_mul_f32_e32 v143, 0x3fb8aa3b, v143
	v_exp_f32_e32 v143, v143
	v_and_b32_e32 v9, 0xffff0000, v9
	v_fma_f32 v142, v143, v142, v9
	v_cvt_pk_bf16_f32 v9, v142, v142
	global_store_short v135, v9, s[66:67]
; __device__ __forceinline__ unsigned pk2(float lo, float hi) { unsigned r; asm("v_cvt_pk_bf16_f32 %0, %1, %2" : "=v"(r) : "v"(lo), "v"(hi)); return r; }
; __device__ __forceinline__ float bflo(unsigned w) { return __uint_as_float(w << 16); }
; __device__ __forceinline__ float bfhi(unsigned w) { return __uint_as_float(w & 0xffff0000u); }
; __device__ __forceinline__ void phase_scan(const Params& p, LAS unsigned char* lds) {
;     ...
; #pragma unroll 8
;         for (int s = 0; s < 128; ++s) { const unsigned lw = __builtin_nontemporal_load(LU + base + (size_t)s * LW); const float la = bflo(lw), u = bfhi(lw); h = __expf(la) * h + u;
;             YL[base + (size_t)s * LW] = (bf16_t)(pk2(h, h) & 0xffffu); }
	v_lshlrev_b32_e32 v140, 16, v10
	v_mul_f32_e32 v140, 0x3fb8aa3b, v140
	v_exp_f32_e32 v140, v140
	v_and_b32_e32 v10, 0xffff0000, v10
	v_fma_f32 v142, v140, v142, v10
	v_cvt_pk_bf16_f32 v10, v142, v142
	global_store_short v136, v10, s[66:67]
	v_lshlrev_b32_e32 v143, 16, v11
	v_mul_f32_e32 v143, 0x3fb8aa3b, v143
	v_exp_f32_e32 v143, v143
	v_and_b32_e32 v11, 0xffff0000, v11
	v_fma_f32 v142, v143, v142, v11
	v_cvt_pk_bf16_f32 v11, v142, v142
	global_store_short v137, v11, s[66:67]
	s_add_u32 s66, s66, 0x4000
	s_addc_u32 s67, s67, 0
	v_lshlrev_b32_e32 v140, 16, v12
	v_mul_f32_e32 v140, 0x3fb8aa3b, v140
	v_exp_f32_e32 v140, v140
	v_and_b32_e32 v12, 0xffff0000, v12
	v_fma_f32 v142, v140, v142, v12
	v_cvt_pk_bf16_f32 v12, v142, v142
	global_store_short v134, v12, s[66:67]
	v_lshlrev_b32_e32 v143, 16, v13
	v_mul_f32_e32 v143, 0x3fb8aa3b, v143
	v_exp_f32_e32 v143, v143
	v_and_b32_e32 v13, 0xffff0000, v13
	v_fma_f32 v142, v143, v142, v13
	v_cvt_pk_bf16_f32 v13, v142, v142
	global_store_short v135, v13, s[66:67]
	v_lshlrev_b32_e32 v140, 16, v14
	v_mul_f32_e32 v140, 0x3fb8aa3b, v140
	v_exp_f32_e32 v140, v140
	v_and_b32_e32 v14, 0xffff0000, v14
	v_fma_f32 v142, v140, v142, v14
	v_cvt_pk_bf16_f32 v14, v142, v142
	global_store_short v136, v14, s[66:67]
	v_lshlrev_b32_e32 v143, 16, v15
	v_mul_f32_e32 v143, 0x3fb8aa3b, v143
	v_exp_f32_e32 v143, v143
	v_and_b32_e32 v15, 0xffff0000, v15
	v_fma_f32 v142, v143, v142, v15
	v_cvt_pk_bf16_f32 v15, v142, v142
	global_store_short v137, v15, s[66:67]
	s_add_u32 s66, s66, 0x4000
	s_addc_u32 s67, s67, 0
	v_lshlrev_b32_e32 v140, 16, v16
	v_mul_f32_e32 v140, 0x3fb8aa3b, v140
	v_exp_f32_e32 v140, v140
	v_and_b32_e32 v16, 0xffff0000, v16
	v_fma_f32 v142, v140, v142, v16
	v_cvt_pk_bf16_f32 v16, v142, v142
	global_store_short v134, v16, s[66:67]
	v_lshlrev_b32_e32 v143, 16, v17
	v_mul_f32_e32 v143, 0x3fb8aa3b, v143
	v_exp_f32_e32 v143, v143
	v_and_b32_e32 v17, 0xffff0000, v17
	v_fma_f32 v142, v143, v142, v17
	v_cvt_pk_bf16_f32 v17, v142, v142
	global_store_short v135, v17, s[66:67]
	v_lshlrev_b32_e32 v140, 16, v18
	v_mul_f32_e32 v140, 0x3fb8aa3b, v140
	v_exp_f32_e32 v140, v140
	v_and_b32_e32 v18, 0xffff0000, v18
	v_fma_f32 v142, v140, v142, v18
	v_cvt_pk_bf16_f32 v18, v142, v142
	global_store_short v136, v18, s[66:67]
	v_lshlrev_b32_e32 v143, 16, v19
	v_mul_f32_e32 v143, 0x3fb8aa3b, v143
	v_exp_f32_e32 v143, v143
	v_and_b32_e32 v19, 0xffff0000, v19
	v_fma_f32 v142, v143, v142, v19
	v_cvt_pk_bf16_f32 v19, v142, v142
	global_store_short v137, v19, s[66:67]
	s_add_u32 s66, s66, 0x4000
	s_addc_u32 s67, s67, 0
	v_lshlrev_b32_e32 v140, 16, v20
	v_mul_f32_e32 v140, 0x3fb8aa3b, v140
	v_exp_f32_e32 v140, v140
	v_and_b32_e32 v20, 0xffff0000, v20
	v_fma_f32 v142, v140, v142, v20
	v_cvt_pk_bf16_f32 v20, v142, v142
	global_store_short v134, v20, s[66:67]
	v_lshlrev_b32_e32 v143, 16, v21
	v_mul_f32_e32 v143, 0x3fb8aa3b, v143
	v_exp_f32_e32 v143, v143
	v_and_b32_e32 v21, 0xffff0000, v21
	v_fma_f32 v142, v143, v142, v21
	v_cvt_pk_bf16_f32 v21, v142, v142
	global_store_short v135, v21, s[66:67]
	v_lshlrev_b32_e32 v140, 16, v22
	v_mul_f32_e32 v140, 0x3fb8aa3b, v140
	v_exp_f32_e32 v140, v140
	v_and_b32_e32 v22, 0xffff0000, v22
	v_fma_f32 v142, v140, v142, v22
	v_cvt_pk_bf16_f32 v22, v142, v142
	global_store_short v136, v22, s[66:67]
	v_lshlrev_b32_e32 v143, 16, v23
	v_mul_f32_e32 v143, 0x3fb8aa3b, v143
	v_exp_f32_e32 v143, v143
	v_and_b32_e32 v23, 0xffff0000, v23
	v_fma_f32 v142, v143, v142, v23
	v_cvt_pk_bf16_f32 v23, v142, v142
	global_store_short v137, v23, s[66:67]
	s_add_u32 s66, s66, 0x4000
	s_addc_u32 s67, s67, 0
	v_lshlrev_b32_e32 v140, 16, v24
	v_mul_f32_e32 v140, 0x3fb8aa3b, v140
	v_exp_f32_e32 v140, v140
	v_and_b32_e32 v24, 0xffff0000, v24
	v_fma_f32 v142, v140, v142, v24
	v_cvt_pk_bf16_f32 v24, v142, v142
	global_store_short v134, v24, s[66:67]
	v_lshlrev_b32_e32 v143, 16, v25
	v_mul_f32_e32 v143, 0x3fb8aa3b, v143
	v_exp_f32_e32 v143, v143
	v_and_b32_e32 v25, 0xffff0000, v25
	v_fma_f32 v142, v143, v142, v25
	v_cvt_pk_bf16_f32 v25, v142, v142
	global_store_short v135, v25, s[66:67]
	v_lshlrev_b32_e32 v140, 16, v26
	v_mul_f32_e32 v140, 0x3fb8aa3b, v140
	v_exp_f32_e32 v140, v140
	v_and_b32_e32 v26, 0xffff0000, v26
	v_fma_f32 v142, v140, v142, v26
	v_cvt_pk_bf16_f32 v26, v142, v142
	global_store_short v136, v26, s[66:67]
	v_lshlrev_b32_e32 v143, 16, v27
	v_mul_f32_e32 v143, 0x3fb8aa3b, v143
	v_exp_f32_e32 v143, v143
	v_and_b32_e32 v27, 0xffff0000, v27
	v_fma_f32 v142, v143, v142, v27
	v_cvt_pk_bf16_f32 v27, v142, v142
	global_store_short v137, v27, s[66:67]
	s_add_u32 s66, s66, 0x4000
	s_addc_u32 s67, s67, 0
	v_lshlrev_b32_e32 v140, 16, v28
	v_mul_f32_e32 v140, 0x3fb8aa3b, v140
	v_exp_f32_e32 v140, v140
	v_and_b32_e32 v28, 0xffff0000, v28
	v_fma_f32 v142, v140, v142, v28
	v_cvt_pk_bf16_f32 v28, v142, v142
	global_store_short v134, v28, s[66:67]
	v_lshlrev_b32_e32 v143, 16, v29
	v_mul_f32_e32 v143, 0x3fb8aa3b, v143
	v_exp_f32_e32 v143, v143
	v_and_b32_e32 v29, 0xffff0000, v29
	v_fma_f32 v142, v143, v142, v29
	v_cvt_pk_bf16_f32 v29, v142, v142
	global_store_short v135, v29, s[66:67]
	v_lshlrev_b32_e32 v140, 16, v30
	v_mul_f32_e32 v140, 0x3fb8aa3b, v140
	v_exp_f32_e32 v140, v140
	v_and_b32_e32 v30, 0xffff0000, v30
	v_fma_f32 v142, v140, v142, v30
	v_cvt_pk_bf16_f32 v30, v142, v142
	global_store_short v136, v30, s[66:67]
	v_lshlrev_b32_e32 v143, 16, v31
	v_mul_f32_e32 v143, 0x3fb8aa3b, v143
	v_exp_f32_e32 v143, v143
	v_and_b32_e32 v31, 0xffff0000, v31
	v_fma_f32 v142, v143, v142, v31
	v_cvt_pk_bf16_f32 v31, v142, v142
	global_store_short v137, v31, s[66:67]
	s_add_u32 s66, s66, 0x4000
	s_addc_u32 s67, s67, 0
	v_lshlrev_b32_e32 v140, 16, v32
; __device__ __forceinline__ unsigned pk2(float lo, float hi) { unsigned r; asm("v_cvt_pk_bf16_f32 %0, %1, %2" : "=v"(r) : "v"(lo), "v"(hi)); return r; }
; __device__ __forceinline__ float bflo(unsigned w) { return __uint_as_float(w << 16); }
; __device__ __forceinline__ float bfhi(unsigned w) { return __uint_as_float(w & 0xffff0000u); }
; __device__ __forceinline__ void phase_scan(const Params& p, LAS unsigned char* lds) {
;     ...
; #pragma unroll 8
;         for (int s = 0; s < 128; ++s) { const unsigned lw = __builtin_nontemporal_load(LU + base + (size_t)s * LW); const float la = bflo(lw), u = bfhi(lw); h = __expf(la) * h + u;
;             YL[base + (size_t)s * LW] = (bf16_t)(pk2(h, h) & 0xffffu); }
	v_mul_f32_e32 v140, 0x3fb8aa3b, v140
	v_exp_f32_e32 v140, v140
	v_and_b32_e32 v32, 0xffff0000, v32
	v_fma_f32 v142, v140, v142, v32
	v_cvt_pk_bf16_f32 v32, v142, v142
	global_store_short v134, v32, s[66:67]
	v_lshlrev_b32_e32 v143, 16, v33
	v_mul_f32_e32 v143, 0x3fb8aa3b, v143
	v_exp_f32_e32 v143, v143
	v_and_b32_e32 v33, 0xffff0000, v33
	v_fma_f32 v142, v143, v142, v33
	v_cvt_pk_bf16_f32 v33, v142, v142
	global_store_short v135, v33, s[66:67]
	v_lshlrev_b32_e32 v140, 16, v34
	v_mul_f32_e32 v140, 0x3fb8aa3b, v140
	v_exp_f32_e32 v140, v140
	v_and_b32_e32 v34, 0xffff0000, v34
	v_fma_f32 v142, v140, v142, v34
	v_cvt_pk_bf16_f32 v34, v142, v142
	global_store_short v136, v34, s[66:67]
	v_lshlrev_b32_e32 v143, 16, v35
	v_mul_f32_e32 v143, 0x3fb8aa3b, v143
	v_exp_f32_e32 v143, v143
	v_and_b32_e32 v35, 0xffff0000, v35
	v_fma_f32 v142, v143, v142, v35
	v_cvt_pk_bf16_f32 v35, v142, v142
	global_store_short v137, v35, s[66:67]
	s_add_u32 s66, s66, 0x4000
	s_addc_u32 s67, s67, 0
	v_lshlrev_b32_e32 v140, 16, v36
	v_mul_f32_e32 v140, 0x3fb8aa3b, v140
	v_exp_f32_e32 v140, v140
	v_and_b32_e32 v36, 0xffff0000, v36
	v_fma_f32 v142, v140, v142, v36
	v_cvt_pk_bf16_f32 v36, v142, v142
	global_store_short v134, v36, s[66:67]
	v_lshlrev_b32_e32 v143, 16, v37
	v_mul_f32_e32 v143, 0x3fb8aa3b, v143
	v_exp_f32_e32 v143, v143
	v_and_b32_e32 v37, 0xffff0000, v37
	v_fma_f32 v142, v143, v142, v37
	v_cvt_pk_bf16_f32 v37, v142, v142
	global_store_short v135, v37, s[66:67]
	v_lshlrev_b32_e32 v140, 16, v38
	v_mul_f32_e32 v140, 0x3fb8aa3b, v140
	v_exp_f32_e32 v140, v140
	v_and_b32_e32 v38, 0xffff0000, v38
	v_fma_f32 v142, v140, v142, v38
	v_cvt_pk_bf16_f32 v38, v142, v142
	global_store_short v136, v38, s[66:67]
	v_lshlrev_b32_e32 v143, 16, v39
	v_mul_f32_e32 v143, 0x3fb8aa3b, v143
	v_exp_f32_e32 v143, v143
	v_and_b32_e32 v39, 0xffff0000, v39
	v_fma_f32 v142, v143, v142, v39
	v_cvt_pk_bf16_f32 v39, v142, v142
	global_store_short v137, v39, s[66:67]
	s_add_u32 s66, s66, 0x4000
	s_addc_u32 s67, s67, 0
	v_lshlrev_b32_e32 v140, 16, v40
	v_mul_f32_e32 v140, 0x3fb8aa3b, v140
	v_exp_f32_e32 v140, v140
	v_and_b32_e32 v40, 0xffff0000, v40
	v_fma_f32 v142, v140, v142, v40
	v_cvt_pk_bf16_f32 v40, v142, v142
	global_store_short v134, v40, s[66:67]
	v_lshlrev_b32_e32 v143, 16, v41
	v_mul_f32_e32 v143, 0x3fb8aa3b, v143
	v_exp_f32_e32 v143, v143
	v_and_b32_e32 v41, 0xffff0000, v41
	v_fma_f32 v142, v143, v142, v41
	v_cvt_pk_bf16_f32 v41, v142, v142
	global_store_short v135, v41, s[66:67]
	v_lshlrev_b32_e32 v140, 16, v42
	v_mul_f32_e32 v140, 0x3fb8aa3b, v140
	v_exp_f32_e32 v140, v140
	v_and_b32_e32 v42, 0xffff0000, v42
	v_fma_f32 v142, v140, v142, v42
	v_cvt_pk_bf16_f32 v42, v142, v142
	global_store_short v136, v42, s[66:67]
	v_lshlrev_b32_e32 v143, 16, v43
	v_mul_f32_e32 v143, 0x3fb8aa3b, v143
	v_exp_f32_e32 v143, v143
	v_and_b32_e32 v43, 0xffff0000, v43
	v_fma_f32 v142, v143, v142, v43
	v_cvt_pk_bf16_f32 v43, v142, v142
	global_store_short v137, v43, s[66:67]
	s_add_u32 s66, s66, 0x4000
	s_addc_u32 s67, s67, 0
	v_lshlrev_b32_e32 v140, 16, v44
	v_mul_f32_e32 v140, 0x3fb8aa3b, v140
	v_exp_f32_e32 v140, v140
	v_and_b32_e32 v44, 0xffff0000, v44
	v_fma_f32 v142, v140, v142, v44
	v_cvt_pk_bf16_f32 v44, v142, v142
	global_store_short v134, v44, s[66:67]
	v_lshlrev_b32_e32 v143, 16, v45
	v_mul_f32_e32 v143, 0x3fb8aa3b, v143
	v_exp_f32_e32 v143, v143
	v_and_b32_e32 v45, 0xffff0000, v45
	v_fma_f32 v142, v143, v142, v45
	v_cvt_pk_bf16_f32 v45, v142, v142
	global_store_short v135, v45, s[66:67]
	v_lshlrev_b32_e32 v140, 16, v46
	v_mul_f32_e32 v140, 0x3fb8aa3b, v140
	v_exp_f32_e32 v140, v140
	v_and_b32_e32 v46, 0xffff0000, v46
	v_fma_f32 v142, v140, v142, v46
	v_cvt_pk_bf16_f32 v46, v142, v142
	global_store_short v136, v46, s[66:67]
	v_lshlrev_b32_e32 v143, 16, v47
	v_mul_f32_e32 v143, 0x3fb8aa3b, v143
	v_exp_f32_e32 v143, v143
	v_and_b32_e32 v47, 0xffff0000, v47
	v_fma_f32 v142, v143, v142, v47
	v_cvt_pk_bf16_f32 v47, v142, v142
	global_store_short v137, v47, s[66:67]
	s_add_u32 s66, s66, 0x4000
	s_addc_u32 s67, s67, 0
	v_lshlrev_b32_e32 v140, 16, v48
	v_mul_f32_e32 v140, 0x3fb8aa3b, v140
	v_exp_f32_e32 v140, v140
	v_and_b32_e32 v48, 0xffff0000, v48
	v_fma_f32 v142, v140, v142, v48
	v_cvt_pk_bf16_f32 v48, v142, v142
	global_store_short v134, v48, s[66:67]
	v_lshlrev_b32_e32 v143, 16, v49
	v_mul_f32_e32 v143, 0x3fb8aa3b, v143
	v_exp_f32_e32 v143, v143
	v_and_b32_e32 v49, 0xffff0000, v49
	v_fma_f32 v142, v143, v142, v49
	v_cvt_pk_bf16_f32 v49, v142, v142
	global_store_short v135, v49, s[66:67]
	v_lshlrev_b32_e32 v140, 16, v50
	v_mul_f32_e32 v140, 0x3fb8aa3b, v140
	v_exp_f32_e32 v140, v140
	v_and_b32_e32 v50, 0xffff0000, v50
	v_fma_f32 v142, v140, v142, v50
	v_cvt_pk_bf16_f32 v50, v142, v142
	global_store_short v136, v50, s[66:67]
	v_lshlrev_b32_e32 v143, 16, v51
	v_mul_f32_e32 v143, 0x3fb8aa3b, v143
	v_exp_f32_e32 v143, v143
	v_and_b32_e32 v51, 0xffff0000, v51
	v_fma_f32 v142, v143, v142, v51
	v_cvt_pk_bf16_f32 v51, v142, v142
	global_store_short v137, v51, s[66:67]
	s_add_u32 s66, s66, 0x4000
	s_addc_u32 s67, s67, 0
	v_lshlrev_b32_e32 v140, 16, v52
	v_mul_f32_e32 v140, 0x3fb8aa3b, v140
	v_exp_f32_e32 v140, v140
	v_and_b32_e32 v52, 0xffff0000, v52
	v_fma_f32 v142, v140, v142, v52
	v_cvt_pk_bf16_f32 v52, v142, v142
	global_store_short v134, v52, s[66:67]
	v_lshlrev_b32_e32 v143, 16, v53
	v_mul_f32_e32 v143, 0x3fb8aa3b, v143
	v_exp_f32_e32 v143, v143
	v_and_b32_e32 v53, 0xffff0000, v53
	v_fma_f32 v142, v143, v142, v53
	v_cvt_pk_bf16_f32 v53, v142, v142
	global_store_short v135, v53, s[66:67]
	v_lshlrev_b32_e32 v140, 16, v54
	v_mul_f32_e32 v140, 0x3fb8aa3b, v140
	v_exp_f32_e32 v140, v140
; __device__ __forceinline__ unsigned pk2(float lo, float hi) { unsigned r; asm("v_cvt_pk_bf16_f32 %0, %1, %2" : "=v"(r) : "v"(lo), "v"(hi)); return r; }
; __device__ __forceinline__ float bflo(unsigned w) { return __uint_as_float(w << 16); }
; __device__ __forceinline__ float bfhi(unsigned w) { return __uint_as_float(w & 0xffff0000u); }
; __device__ __forceinline__ void phase_scan(const Params& p, LAS unsigned char* lds) {
;     ...
; #pragma unroll 8
;         for (int s = 0; s < 128; ++s) { const unsigned lw = __builtin_nontemporal_load(LU + base + (size_t)s * LW); const float la = bflo(lw), u = bfhi(lw); h = __expf(la) * h + u;
;             YL[base + (size_t)s * LW] = (bf16_t)(pk2(h, h) & 0xffffu); }
	v_and_b32_e32 v54, 0xffff0000, v54
	v_fma_f32 v142, v140, v142, v54
	v_cvt_pk_bf16_f32 v54, v142, v142
	global_store_short v136, v54, s[66:67]
	v_lshlrev_b32_e32 v143, 16, v55
	v_mul_f32_e32 v143, 0x3fb8aa3b, v143
	v_exp_f32_e32 v143, v143
	v_and_b32_e32 v55, 0xffff0000, v55
	v_fma_f32 v142, v143, v142, v55
	v_cvt_pk_bf16_f32 v55, v142, v142
	global_store_short v137, v55, s[66:67]
	s_add_u32 s66, s66, 0x4000
	s_addc_u32 s67, s67, 0
	v_lshlrev_b32_e32 v140, 16, v56
	v_mul_f32_e32 v140, 0x3fb8aa3b, v140
	v_exp_f32_e32 v140, v140
	v_and_b32_e32 v56, 0xffff0000, v56
	v_fma_f32 v142, v140, v142, v56
	v_cvt_pk_bf16_f32 v56, v142, v142
	global_store_short v134, v56, s[66:67]
	v_lshlrev_b32_e32 v143, 16, v57
	v_mul_f32_e32 v143, 0x3fb8aa3b, v143
	v_exp_f32_e32 v143, v143
	v_and_b32_e32 v57, 0xffff0000, v57
	v_fma_f32 v142, v143, v142, v57
	v_cvt_pk_bf16_f32 v57, v142, v142
	global_store_short v135, v57, s[66:67]
	v_lshlrev_b32_e32 v140, 16, v58
	v_mul_f32_e32 v140, 0x3fb8aa3b, v140
	v_exp_f32_e32 v140, v140
	v_and_b32_e32 v58, 0xffff0000, v58
	v_fma_f32 v142, v140, v142, v58
	v_cvt_pk_bf16_f32 v58, v142, v142
	global_store_short v136, v58, s[66:67]
	v_lshlrev_b32_e32 v143, 16, v59
	v_mul_f32_e32 v143, 0x3fb8aa3b, v143
	v_exp_f32_e32 v143, v143
	v_and_b32_e32 v59, 0xffff0000, v59
	v_fma_f32 v142, v143, v142, v59
	v_cvt_pk_bf16_f32 v59, v142, v142
	global_store_short v137, v59, s[66:67]
	s_add_u32 s66, s66, 0x4000
	s_addc_u32 s67, s67, 0
	v_lshlrev_b32_e32 v140, 16, v60
	v_mul_f32_e32 v140, 0x3fb8aa3b, v140
	v_exp_f32_e32 v140, v140
	v_and_b32_e32 v60, 0xffff0000, v60
	v_fma_f32 v142, v140, v142, v60
	v_cvt_pk_bf16_f32 v60, v142, v142
	global_store_short v134, v60, s[66:67]
	v_lshlrev_b32_e32 v143, 16, v61
	v_mul_f32_e32 v143, 0x3fb8aa3b, v143
	v_exp_f32_e32 v143, v143
	v_and_b32_e32 v61, 0xffff0000, v61
	v_fma_f32 v142, v143, v142, v61
	v_cvt_pk_bf16_f32 v61, v142, v142
	global_store_short v135, v61, s[66:67]
	v_lshlrev_b32_e32 v140, 16, v62
	v_mul_f32_e32 v140, 0x3fb8aa3b, v140
	v_exp_f32_e32 v140, v140
	v_and_b32_e32 v62, 0xffff0000, v62
	v_fma_f32 v142, v140, v142, v62
	v_cvt_pk_bf16_f32 v62, v142, v142
	global_store_short v136, v62, s[66:67]
	v_lshlrev_b32_e32 v143, 16, v63
	v_mul_f32_e32 v143, 0x3fb8aa3b, v143
	v_exp_f32_e32 v143, v143
	v_and_b32_e32 v63, 0xffff0000, v63
	v_fma_f32 v142, v143, v142, v63
	v_cvt_pk_bf16_f32 v63, v142, v142
	global_store_short v137, v63, s[66:67]
	s_add_u32 s66, s66, 0x4000
	s_addc_u32 s67, s67, 0
	v_lshlrev_b32_e32 v140, 16, v64
	v_mul_f32_e32 v140, 0x3fb8aa3b, v140
	v_exp_f32_e32 v140, v140
	v_and_b32_e32 v64, 0xffff0000, v64
	v_fma_f32 v142, v140, v142, v64
	v_cvt_pk_bf16_f32 v64, v142, v142
	global_store_short v134, v64, s[66:67]
	v_lshlrev_b32_e32 v143, 16, v65
	v_mul_f32_e32 v143, 0x3fb8aa3b, v143
	v_exp_f32_e32 v143, v143
	v_and_b32_e32 v65, 0xffff0000, v65
	v_fma_f32 v142, v143, v142, v65
	v_cvt_pk_bf16_f32 v65, v142, v142
	global_store_short v135, v65, s[66:67]
	v_lshlrev_b32_e32 v140, 16, v66
	v_mul_f32_e32 v140, 0x3fb8aa3b, v140
	v_exp_f32_e32 v140, v140
	v_and_b32_e32 v66, 0xffff0000, v66
	v_fma_f32 v142, v140, v142, v66
	v_cvt_pk_bf16_f32 v66, v142, v142
	global_store_short v136, v66, s[66:67]
	v_lshlrev_b32_e32 v143, 16, v67
	v_mul_f32_e32 v143, 0x3fb8aa3b, v143
	v_exp_f32_e32 v143, v143
	v_and_b32_e32 v67, 0xffff0000, v67
	v_fma_f32 v142, v143, v142, v67
	v_cvt_pk_bf16_f32 v67, v142, v142
	global_store_short v137, v67, s[66:67]
	s_add_u32 s66, s66, 0x4000
	s_addc_u32 s67, s67, 0
	v_lshlrev_b32_e32 v140, 16, v68
	v_mul_f32_e32 v140, 0x3fb8aa3b, v140
	v_exp_f32_e32 v140, v140
	v_and_b32_e32 v68, 0xffff0000, v68
	v_fma_f32 v142, v140, v142, v68
	v_cvt_pk_bf16_f32 v68, v142, v142
	global_store_short v134, v68, s[66:67]
	v_lshlrev_b32_e32 v143, 16, v69
	v_mul_f32_e32 v143, 0x3fb8aa3b, v143
	v_exp_f32_e32 v143, v143
	v_and_b32_e32 v69, 0xffff0000, v69
	v_fma_f32 v142, v143, v142, v69
	v_cvt_pk_bf16_f32 v69, v142, v142
	global_store_short v135, v69, s[66:67]
	v_lshlrev_b32_e32 v140, 16, v70
	v_mul_f32_e32 v140, 0x3fb8aa3b, v140
	v_exp_f32_e32 v140, v140
	v_and_b32_e32 v70, 0xffff0000, v70
	v_fma_f32 v142, v140, v142, v70
	v_cvt_pk_bf16_f32 v70, v142, v142
	global_store_short v136, v70, s[66:67]
	v_lshlrev_b32_e32 v143, 16, v71
	v_mul_f32_e32 v143, 0x3fb8aa3b, v143
	v_exp_f32_e32 v143, v143
	v_and_b32_e32 v71, 0xffff0000, v71
	v_fma_f32 v142, v143, v142, v71
	v_cvt_pk_bf16_f32 v71, v142, v142
	global_store_short v137, v71, s[66:67]
	s_add_u32 s66, s66, 0x4000
	s_addc_u32 s67, s67, 0
	v_lshlrev_b32_e32 v140, 16, v72
	v_mul_f32_e32 v140, 0x3fb8aa3b, v140
	v_exp_f32_e32 v140, v140
	v_and_b32_e32 v72, 0xffff0000, v72
	v_fma_f32 v142, v140, v142, v72
	v_cvt_pk_bf16_f32 v72, v142, v142
	global_store_short v134, v72, s[66:67]
	v_lshlrev_b32_e32 v143, 16, v73
	v_mul_f32_e32 v143, 0x3fb8aa3b, v143
	v_exp_f32_e32 v143, v143
	v_and_b32_e32 v73, 0xffff0000, v73
	v_fma_f32 v142, v143, v142, v73
	v_cvt_pk_bf16_f32 v73, v142, v142
	global_store_short v135, v73, s[66:67]
	v_lshlrev_b32_e32 v140, 16, v74
	v_mul_f32_e32 v140, 0x3fb8aa3b, v140
	v_exp_f32_e32 v140, v140
	v_and_b32_e32 v74, 0xffff0000, v74
	v_fma_f32 v142, v140, v142, v74
	v_cvt_pk_bf16_f32 v74, v142, v142
	global_store_short v136, v74, s[66:67]
	v_lshlrev_b32_e32 v143, 16, v75
	v_mul_f32_e32 v143, 0x3fb8aa3b, v143
	v_exp_f32_e32 v143, v143
	v_and_b32_e32 v75, 0xffff0000, v75
	v_fma_f32 v142, v143, v142, v75
	v_cvt_pk_bf16_f32 v75, v142, v142
	global_store_short v137, v75, s[66:67]
	s_add_u32 s66, s66, 0x4000
	s_addc_u32 s67, s67, 0
	v_lshlrev_b32_e32 v140, 16, v76
	v_mul_f32_e32 v140, 0x3fb8aa3b, v140
	v_exp_f32_e32 v140, v140
	v_and_b32_e32 v76, 0xffff0000, v76
; __device__ __forceinline__ unsigned pk2(float lo, float hi) { unsigned r; asm("v_cvt_pk_bf16_f32 %0, %1, %2" : "=v"(r) : "v"(lo), "v"(hi)); return r; }
; __device__ __forceinline__ float bflo(unsigned w) { return __uint_as_float(w << 16); }
; __device__ __forceinline__ float bfhi(unsigned w) { return __uint_as_float(w & 0xffff0000u); }
; __device__ __forceinline__ void phase_scan(const Params& p, LAS unsigned char* lds) {
;     ...
; #pragma unroll 8
;         for (int s = 0; s < 128; ++s) { const unsigned lw = __builtin_nontemporal_load(LU + base + (size_t)s * LW); const float la = bflo(lw), u = bfhi(lw); h = __expf(la) * h + u;
;             YL[base + (size_t)s * LW] = (bf16_t)(pk2(h, h) & 0xffffu); }
	v_fma_f32 v142, v140, v142, v76
	v_cvt_pk_bf16_f32 v76, v142, v142
	global_store_short v134, v76, s[66:67]
	v_lshlrev_b32_e32 v143, 16, v77
	v_mul_f32_e32 v143, 0x3fb8aa3b, v143
	v_exp_f32_e32 v143, v143
	v_and_b32_e32 v77, 0xffff0000, v77
	v_fma_f32 v142, v143, v142, v77
	v_cvt_pk_bf16_f32 v77, v142, v142
	global_store_short v135, v77, s[66:67]
	v_lshlrev_b32_e32 v140, 16, v78
	v_mul_f32_e32 v140, 0x3fb8aa3b, v140
	v_exp_f32_e32 v140, v140
	v_and_b32_e32 v78, 0xffff0000, v78
	v_fma_f32 v142, v140, v142, v78
	v_cvt_pk_bf16_f32 v78, v142, v142
	global_store_short v136, v78, s[66:67]
	v_lshlrev_b32_e32 v143, 16, v79
	v_mul_f32_e32 v143, 0x3fb8aa3b, v143
	v_exp_f32_e32 v143, v143
	v_and_b32_e32 v79, 0xffff0000, v79
	v_fma_f32 v142, v143, v142, v79
	v_cvt_pk_bf16_f32 v79, v142, v142
	global_store_short v137, v79, s[66:67]
	s_add_u32 s66, s66, 0x4000
	s_addc_u32 s67, s67, 0
	v_lshlrev_b32_e32 v140, 16, v80
	v_mul_f32_e32 v140, 0x3fb8aa3b, v140
	v_exp_f32_e32 v140, v140
	v_and_b32_e32 v80, 0xffff0000, v80
	v_fma_f32 v142, v140, v142, v80
	v_cvt_pk_bf16_f32 v80, v142, v142
	global_store_short v134, v80, s[66:67]
	v_lshlrev_b32_e32 v143, 16, v81
	v_mul_f32_e32 v143, 0x3fb8aa3b, v143
	v_exp_f32_e32 v143, v143
	v_and_b32_e32 v81, 0xffff0000, v81
	v_fma_f32 v142, v143, v142, v81
	v_cvt_pk_bf16_f32 v81, v142, v142
	global_store_short v135, v81, s[66:67]
	v_lshlrev_b32_e32 v140, 16, v82
	v_mul_f32_e32 v140, 0x3fb8aa3b, v140
	v_exp_f32_e32 v140, v140
	v_and_b32_e32 v82, 0xffff0000, v82
	v_fma_f32 v142, v140, v142, v82
	v_cvt_pk_bf16_f32 v82, v142, v142
	global_store_short v136, v82, s[66:67]
	v_lshlrev_b32_e32 v143, 16, v83
	v_mul_f32_e32 v143, 0x3fb8aa3b, v143
	v_exp_f32_e32 v143, v143
	v_and_b32_e32 v83, 0xffff0000, v83
	v_fma_f32 v142, v143, v142, v83
	v_cvt_pk_bf16_f32 v83, v142, v142
	global_store_short v137, v83, s[66:67]
	s_add_u32 s66, s66, 0x4000
	s_addc_u32 s67, s67, 0
	v_lshlrev_b32_e32 v140, 16, v84
	v_mul_f32_e32 v140, 0x3fb8aa3b, v140
	v_exp_f32_e32 v140, v140
	v_and_b32_e32 v84, 0xffff0000, v84
	v_fma_f32 v142, v140, v142, v84
	v_cvt_pk_bf16_f32 v84, v142, v142
	global_store_short v134, v84, s[66:67]
	v_lshlrev_b32_e32 v143, 16, v85
	v_mul_f32_e32 v143, 0x3fb8aa3b, v143
	v_exp_f32_e32 v143, v143
	v_and_b32_e32 v85, 0xffff0000, v85
	v_fma_f32 v142, v143, v142, v85
	v_cvt_pk_bf16_f32 v85, v142, v142
	global_store_short v135, v85, s[66:67]
	v_lshlrev_b32_e32 v140, 16, v86
	v_mul_f32_e32 v140, 0x3fb8aa3b, v140
	v_exp_f32_e32 v140, v140
	v_and_b32_e32 v86, 0xffff0000, v86
	v_fma_f32 v142, v140, v142, v86
	v_cvt_pk_bf16_f32 v86, v142, v142
	global_store_short v136, v86, s[66:67]
	v_lshlrev_b32_e32 v143, 16, v87
	v_mul_f32_e32 v143, 0x3fb8aa3b, v143
	v_exp_f32_e32 v143, v143
	v_and_b32_e32 v87, 0xffff0000, v87
	v_fma_f32 v142, v143, v142, v87
	v_cvt_pk_bf16_f32 v87, v142, v142
	global_store_short v137, v87, s[66:67]
	s_add_u32 s66, s66, 0x4000
	s_addc_u32 s67, s67, 0
	v_lshlrev_b32_e32 v140, 16, v88
	v_mul_f32_e32 v140, 0x3fb8aa3b, v140
	v_exp_f32_e32 v140, v140
	v_and_b32_e32 v88, 0xffff0000, v88
	v_fma_f32 v142, v140, v142, v88
	v_cvt_pk_bf16_f32 v88, v142, v142
	global_store_short v134, v88, s[66:67]
	v_lshlrev_b32_e32 v143, 16, v89
	v_mul_f32_e32 v143, 0x3fb8aa3b, v143
	v_exp_f32_e32 v143, v143
	v_and_b32_e32 v89, 0xffff0000, v89
	v_fma_f32 v142, v143, v142, v89
	v_cvt_pk_bf16_f32 v89, v142, v142
	global_store_short v135, v89, s[66:67]
	v_lshlrev_b32_e32 v140, 16, v90
	v_mul_f32_e32 v140, 0x3fb8aa3b, v140
	v_exp_f32_e32 v140, v140
	v_and_b32_e32 v90, 0xffff0000, v90
	v_fma_f32 v142, v140, v142, v90
	v_cvt_pk_bf16_f32 v90, v142, v142
	global_store_short v136, v90, s[66:67]
	v_lshlrev_b32_e32 v143, 16, v91
	v_mul_f32_e32 v143, 0x3fb8aa3b, v143
	v_exp_f32_e32 v143, v143
	v_and_b32_e32 v91, 0xffff0000, v91
	v_fma_f32 v142, v143, v142, v91
	v_cvt_pk_bf16_f32 v91, v142, v142
	global_store_short v137, v91, s[66:67]
	s_add_u32 s66, s66, 0x4000
	s_addc_u32 s67, s67, 0
	v_lshlrev_b32_e32 v140, 16, v92
	v_mul_f32_e32 v140, 0x3fb8aa3b, v140
	v_exp_f32_e32 v140, v140
	v_and_b32_e32 v92, 0xffff0000, v92
	v_fma_f32 v142, v140, v142, v92
	v_cvt_pk_bf16_f32 v92, v142, v142
	global_store_short v134, v92, s[66:67]
	v_lshlrev_b32_e32 v143, 16, v93
	v_mul_f32_e32 v143, 0x3fb8aa3b, v143
	v_exp_f32_e32 v143, v143
	v_and_b32_e32 v93, 0xffff0000, v93
	v_fma_f32 v142, v143, v142, v93
	v_cvt_pk_bf16_f32 v93, v142, v142
	global_store_short v135, v93, s[66:67]
	v_lshlrev_b32_e32 v140, 16, v94
	v_mul_f32_e32 v140, 0x3fb8aa3b, v140
	v_exp_f32_e32 v140, v140
	v_and_b32_e32 v94, 0xffff0000, v94
	v_fma_f32 v142, v140, v142, v94
	v_cvt_pk_bf16_f32 v94, v142, v142
	global_store_short v136, v94, s[66:67]
	v_lshlrev_b32_e32 v143, 16, v95
	v_mul_f32_e32 v143, 0x3fb8aa3b, v143
	v_exp_f32_e32 v143, v143
	v_and_b32_e32 v95, 0xffff0000, v95
	v_fma_f32 v142, v143, v142, v95
	v_cvt_pk_bf16_f32 v95, v142, v142
	global_store_short v137, v95, s[66:67]
	s_add_u32 s66, s66, 0x4000
	s_addc_u32 s67, s67, 0
	v_lshlrev_b32_e32 v140, 16, v96
	v_mul_f32_e32 v140, 0x3fb8aa3b, v140
	v_exp_f32_e32 v140, v140
	v_and_b32_e32 v96, 0xffff0000, v96
	v_fma_f32 v142, v140, v142, v96
	v_cvt_pk_bf16_f32 v96, v142, v142
	global_store_short v134, v96, s[66:67]
	v_lshlrev_b32_e32 v143, 16, v97
	v_mul_f32_e32 v143, 0x3fb8aa3b, v143
	v_exp_f32_e32 v143, v143
	v_and_b32_e32 v97, 0xffff0000, v97
	v_fma_f32 v142, v143, v142, v97
	v_cvt_pk_bf16_f32 v97, v142, v142
	global_store_short v135, v97, s[66:67]
	v_lshlrev_b32_e32 v140, 16, v98
	v_mul_f32_e32 v140, 0x3fb8aa3b, v140
	v_exp_f32_e32 v140, v140
	v_and_b32_e32 v98, 0xffff0000, v98
	v_fma_f32 v142, v140, v142, v98
	v_cvt_pk_bf16_f32 v98, v142, v142
; __device__ __forceinline__ unsigned pk2(float lo, float hi) { unsigned r; asm("v_cvt_pk_bf16_f32 %0, %1, %2" : "=v"(r) : "v"(lo), "v"(hi)); return r; }
; __device__ __forceinline__ float bflo(unsigned w) { return __uint_as_float(w << 16); }
; __device__ __forceinline__ float bfhi(unsigned w) { return __uint_as_float(w & 0xffff0000u); }
; __device__ __forceinline__ void phase_scan(const Params& p, LAS unsigned char* lds) {
;     ...
; #pragma unroll 8
;         for (int s = 0; s < 128; ++s) { const unsigned lw = __builtin_nontemporal_load(LU + base + (size_t)s * LW); const float la = bflo(lw), u = bfhi(lw); h = __expf(la) * h + u;
;             YL[base + (size_t)s * LW] = (bf16_t)(pk2(h, h) & 0xffffu); }
	global_store_short v136, v98, s[66:67]
	v_lshlrev_b32_e32 v143, 16, v99
	v_mul_f32_e32 v143, 0x3fb8aa3b, v143
	v_exp_f32_e32 v143, v143
	v_and_b32_e32 v99, 0xffff0000, v99
	v_fma_f32 v142, v143, v142, v99
	v_cvt_pk_bf16_f32 v99, v142, v142
	global_store_short v137, v99, s[66:67]
	s_add_u32 s66, s66, 0x4000
	s_addc_u32 s67, s67, 0
	v_lshlrev_b32_e32 v140, 16, v100
	v_mul_f32_e32 v140, 0x3fb8aa3b, v140
	v_exp_f32_e32 v140, v140
	v_and_b32_e32 v100, 0xffff0000, v100
	v_fma_f32 v142, v140, v142, v100
	v_cvt_pk_bf16_f32 v100, v142, v142
	global_store_short v134, v100, s[66:67]
	v_lshlrev_b32_e32 v143, 16, v101
	v_mul_f32_e32 v143, 0x3fb8aa3b, v143
	v_exp_f32_e32 v143, v143
	v_and_b32_e32 v101, 0xffff0000, v101
	v_fma_f32 v142, v143, v142, v101
	v_cvt_pk_bf16_f32 v101, v142, v142
	global_store_short v135, v101, s[66:67]
	v_lshlrev_b32_e32 v140, 16, v102
	v_mul_f32_e32 v140, 0x3fb8aa3b, v140
	v_exp_f32_e32 v140, v140
	v_and_b32_e32 v102, 0xffff0000, v102
	v_fma_f32 v142, v140, v142, v102
	v_cvt_pk_bf16_f32 v102, v142, v142
	global_store_short v136, v102, s[66:67]
	v_lshlrev_b32_e32 v143, 16, v103
	v_mul_f32_e32 v143, 0x3fb8aa3b, v143
	v_exp_f32_e32 v143, v143
	v_and_b32_e32 v103, 0xffff0000, v103
	v_fma_f32 v142, v143, v142, v103
	v_cvt_pk_bf16_f32 v103, v142, v142
	global_store_short v137, v103, s[66:67]
	s_add_u32 s66, s66, 0x4000
	s_addc_u32 s67, s67, 0
	v_lshlrev_b32_e32 v140, 16, v104
	v_mul_f32_e32 v140, 0x3fb8aa3b, v140
	v_exp_f32_e32 v140, v140
	v_and_b32_e32 v104, 0xffff0000, v104
	v_fma_f32 v142, v140, v142, v104
	v_cvt_pk_bf16_f32 v104, v142, v142
	global_store_short v134, v104, s[66:67]
	v_lshlrev_b32_e32 v143, 16, v105
	v_mul_f32_e32 v143, 0x3fb8aa3b, v143
	v_exp_f32_e32 v143, v143
	v_and_b32_e32 v105, 0xffff0000, v105
	v_fma_f32 v142, v143, v142, v105
	v_cvt_pk_bf16_f32 v105, v142, v142
	global_store_short v135, v105, s[66:67]
	v_lshlrev_b32_e32 v140, 16, v106
	v_mul_f32_e32 v140, 0x3fb8aa3b, v140
	v_exp_f32_e32 v140, v140
	v_and_b32_e32 v106, 0xffff0000, v106
	v_fma_f32 v142, v140, v142, v106
	v_cvt_pk_bf16_f32 v106, v142, v142
	global_store_short v136, v106, s[66:67]
	v_lshlrev_b32_e32 v143, 16, v107
	v_mul_f32_e32 v143, 0x3fb8aa3b, v143
	v_exp_f32_e32 v143, v143
	v_and_b32_e32 v107, 0xffff0000, v107
	v_fma_f32 v142, v143, v142, v107
	v_cvt_pk_bf16_f32 v107, v142, v142
	global_store_short v137, v107, s[66:67]
	s_add_u32 s66, s66, 0x4000
	s_addc_u32 s67, s67, 0
	v_lshlrev_b32_e32 v140, 16, v108
	v_mul_f32_e32 v140, 0x3fb8aa3b, v140
	v_exp_f32_e32 v140, v140
	v_and_b32_e32 v108, 0xffff0000, v108
	v_fma_f32 v142, v140, v142, v108
	v_cvt_pk_bf16_f32 v108, v142, v142
	global_store_short v134, v108, s[66:67]
	v_lshlrev_b32_e32 v143, 16, v109
	v_mul_f32_e32 v143, 0x3fb8aa3b, v143
	v_exp_f32_e32 v143, v143
	v_and_b32_e32 v109, 0xffff0000, v109
	v_fma_f32 v142, v143, v142, v109
	v_cvt_pk_bf16_f32 v109, v142, v142
	global_store_short v135, v109, s[66:67]
	v_lshlrev_b32_e32 v140, 16, v110
	v_mul_f32_e32 v140, 0x3fb8aa3b, v140
	v_exp_f32_e32 v140, v140
	v_and_b32_e32 v110, 0xffff0000, v110
	v_fma_f32 v142, v140, v142, v110
	v_cvt_pk_bf16_f32 v110, v142, v142
	global_store_short v136, v110, s[66:67]
	v_lshlrev_b32_e32 v143, 16, v111
	v_mul_f32_e32 v143, 0x3fb8aa3b, v143
	v_exp_f32_e32 v143, v143
	v_and_b32_e32 v111, 0xffff0000, v111
	v_fma_f32 v142, v143, v142, v111
	v_cvt_pk_bf16_f32 v111, v142, v142
	global_store_short v137, v111, s[66:67]
	s_add_u32 s66, s66, 0x4000
	s_addc_u32 s67, s67, 0
	v_lshlrev_b32_e32 v140, 16, v112
	v_mul_f32_e32 v140, 0x3fb8aa3b, v140
	v_exp_f32_e32 v140, v140
	v_and_b32_e32 v112, 0xffff0000, v112
	v_fma_f32 v142, v140, v142, v112
	v_cvt_pk_bf16_f32 v112, v142, v142
	global_store_short v134, v112, s[66:67]
	v_lshlrev_b32_e32 v143, 16, v113
	v_mul_f32_e32 v143, 0x3fb8aa3b, v143
	v_exp_f32_e32 v143, v143
	v_and_b32_e32 v113, 0xffff0000, v113
	v_fma_f32 v142, v143, v142, v113
; __device__ __forceinline__ unsigned pk2(float lo, float hi) { unsigned r; asm("v_cvt_pk_bf16_f32 %0, %1, %2" : "=v"(r) : "v"(lo), "v"(hi)); return r; }
; __device__ __forceinline__ float bflo(unsigned w) { return __uint_as_float(w << 16); }
; __device__ __forceinline__ float bfhi(unsigned w) { return __uint_as_float(w & 0xffff0000u); }
; __device__ __forceinline__ void phase_scan(const Params& p, LAS unsigned char* lds) {
;     ...
; #pragma unroll 8
;         for (int s = 0; s < 128; ++s) { const unsigned lw = __builtin_nontemporal_load(LU + base + (size_t)s * LW); const float la = bflo(lw), u = bfhi(lw); h = __expf(la) * h + u;
;             YL[base + (size_t)s * LW] = (bf16_t)(pk2(h, h) & 0xffffu); }
;         if (chunk == 15) p.out[O_LHP + b * LW + ch] = h;
	v_cvt_pk_bf16_f32 v113, v142, v142
	global_store_short v135, v113, s[66:67]
	v_lshlrev_b32_e32 v140, 16, v114
	v_mul_f32_e32 v140, 0x3fb8aa3b, v140
	v_exp_f32_e32 v140, v140
	v_and_b32_e32 v114, 0xffff0000, v114
	v_fma_f32 v142, v140, v142, v114
	v_cvt_pk_bf16_f32 v114, v142, v142
	global_store_short v136, v114, s[66:67]
	v_lshlrev_b32_e32 v143, 16, v115
	v_mul_f32_e32 v143, 0x3fb8aa3b, v143
	v_exp_f32_e32 v143, v143
	v_and_b32_e32 v115, 0xffff0000, v115
	v_fma_f32 v142, v143, v142, v115
	v_cvt_pk_bf16_f32 v115, v142, v142
	global_store_short v137, v115, s[66:67]
	s_add_u32 s66, s66, 0x4000
	s_addc_u32 s67, s67, 0
	v_lshlrev_b32_e32 v140, 16, v116
	v_mul_f32_e32 v140, 0x3fb8aa3b, v140
	v_exp_f32_e32 v140, v140
	v_and_b32_e32 v116, 0xffff0000, v116
	v_fma_f32 v142, v140, v142, v116
	v_cvt_pk_bf16_f32 v116, v142, v142
	global_store_short v134, v116, s[66:67]
	v_lshlrev_b32_e32 v143, 16, v117
	v_mul_f32_e32 v143, 0x3fb8aa3b, v143
	v_exp_f32_e32 v143, v143
	v_and_b32_e32 v117, 0xffff0000, v117
	v_fma_f32 v142, v143, v142, v117
	v_cvt_pk_bf16_f32 v117, v142, v142
	global_store_short v135, v117, s[66:67]
	v_lshlrev_b32_e32 v140, 16, v118
	v_mul_f32_e32 v140, 0x3fb8aa3b, v140
	v_exp_f32_e32 v140, v140
	v_and_b32_e32 v118, 0xffff0000, v118
	v_fma_f32 v142, v140, v142, v118
	v_cvt_pk_bf16_f32 v118, v142, v142
	global_store_short v136, v118, s[66:67]
	v_lshlrev_b32_e32 v143, 16, v119
	v_mul_f32_e32 v143, 0x3fb8aa3b, v143
	v_exp_f32_e32 v143, v143
	v_and_b32_e32 v119, 0xffff0000, v119
	v_fma_f32 v142, v143, v142, v119
	v_cvt_pk_bf16_f32 v119, v142, v142
	global_store_short v137, v119, s[66:67]
	s_add_u32 s66, s66, 0x4000
	s_addc_u32 s67, s67, 0
	v_lshlrev_b32_e32 v140, 16, v120
	v_mul_f32_e32 v140, 0x3fb8aa3b, v140
	v_exp_f32_e32 v140, v140
	v_and_b32_e32 v120, 0xffff0000, v120
	v_fma_f32 v142, v140, v142, v120
	v_cvt_pk_bf16_f32 v120, v142, v142
	global_store_short v134, v120, s[66:67]
	v_lshlrev_b32_e32 v143, 16, v121
	v_mul_f32_e32 v143, 0x3fb8aa3b, v143
	v_exp_f32_e32 v143, v143
	v_and_b32_e32 v121, 0xffff0000, v121
	v_fma_f32 v142, v143, v142, v121
	v_cvt_pk_bf16_f32 v121, v142, v142
	global_store_short v135, v121, s[66:67]
	v_lshlrev_b32_e32 v140, 16, v122
	v_mul_f32_e32 v140, 0x3fb8aa3b, v140
	v_exp_f32_e32 v140, v140
	v_and_b32_e32 v122, 0xffff0000, v122
	v_fma_f32 v142, v140, v142, v122
	v_cvt_pk_bf16_f32 v122, v142, v142
	global_store_short v136, v122, s[66:67]
	v_lshlrev_b32_e32 v143, 16, v123
	v_mul_f32_e32 v143, 0x3fb8aa3b, v143
	v_exp_f32_e32 v143, v143
	v_and_b32_e32 v123, 0xffff0000, v123
	v_fma_f32 v142, v143, v142, v123
	v_cvt_pk_bf16_f32 v123, v142, v142
	global_store_short v137, v123, s[66:67]
	s_add_u32 s66, s66, 0x4000
	s_addc_u32 s67, s67, 0
	v_lshlrev_b32_e32 v140, 16, v124
	v_mul_f32_e32 v140, 0x3fb8aa3b, v140
	v_exp_f32_e32 v140, v140
	v_and_b32_e32 v124, 0xffff0000, v124
	v_fma_f32 v142, v140, v142, v124
	v_cvt_pk_bf16_f32 v124, v142, v142
	global_store_short v134, v124, s[66:67]
	v_lshlrev_b32_e32 v143, 16, v125
	v_mul_f32_e32 v143, 0x3fb8aa3b, v143
	v_exp_f32_e32 v143, v143
	v_and_b32_e32 v125, 0xffff0000, v125
	v_fma_f32 v142, v143, v142, v125
	v_cvt_pk_bf16_f32 v125, v142, v142
	global_store_short v135, v125, s[66:67]
	v_lshlrev_b32_e32 v140, 16, v126
	v_mul_f32_e32 v140, 0x3fb8aa3b, v140
	v_exp_f32_e32 v140, v140
	v_and_b32_e32 v126, 0xffff0000, v126
	v_fma_f32 v142, v140, v142, v126
	v_cvt_pk_bf16_f32 v126, v142, v142
	global_store_short v136, v126, s[66:67]
	v_lshlrev_b32_e32 v143, 16, v127
	v_mul_f32_e32 v143, 0x3fb8aa3b, v143
	v_exp_f32_e32 v143, v143
	v_and_b32_e32 v127, 0xffff0000, v127
	v_fma_f32 v142, v143, v142, v127
	v_cvt_pk_bf16_f32 v127, v142, v142
	global_store_short v137, v127, s[66:67]
	v_cmp_eq_u32_e64 s[60:61], 15, v128
	s_and_saveexec_b64 s[62:63], s[60:61]
	s_cbranch_execz .Lscan_nolast
	global_store_dword v148, v142, s[70:71]

; __device__ __forceinline__ unsigned pk2(float lo, float hi) { unsigned r; asm("v_cvt_pk_bf16_f32 %0, %1, %2" : "=v"(r) : "v"(lo), "v"(hi)); return r; }
; __device__ __forceinline__ float bflo(unsigned w) { return __uint_as_float(w << 16); }
; __device__ __forceinline__ float bfhi(unsigned w) { return __uint_as_float(w & 0xffff0000u); }
; __device__ __forceinline__ void phase_scan(const Params& p, LAS unsigned char* lds) {
;     ...
;     const int gt = blockIdx.x * NTHREADS + tid, NGT = gridDim.x * NTHREADS;
;     for (int i = gt; i < 128 * LW; i += NGT) { const int b = i >> 11, ch = i & 2047;
;         float h = p.in[I_SLH][i]; const size_t base = (size_t)(MPROMPT + b * 8) * LW + ch;
; #pragma unroll
;         for (int s = 0; s < 8; ++s) { const unsigned lw = LU[base + (size_t)s * LW]; const float la = bflo(lw), u = bfhi(lw); h = __expf(la) * h + u;
;             YL[base + (size_t)s * LW] = (bf16_t)(pk2(h, h) & 0xffffu); }
;         p.out[O_LHS + i] = h; }
.LBB0_877:
	s_mov_b64 s[6:7], exec
	s_branch .LBB0_880
